# sample attention P.V on f32 matrix cores (v_mfma_f32_16x16x4_f32, P transposed through LDS) instead of readlane+fmac; prompt mask/bias uses v_mul+v_fma instead of mov+pk_mul+sub (bit-identical)
# speedup vs baseline: 1.0167x; 1.0013x over previous
.LBB0_685:
	s_add_i32 s27, s26, 32
	s_cmpk_eq_i32 s26, 0x60
	s_cselect_b32 s30, s26, s27
	v_add_u32_e32 v4, s30, v126
	v_ashrrev_i32_e32 v5, 31, v4
	v_lshlrev_b64 v[4:5], 11, v[4:5]
	v_lshl_add_u64 v[4:5], v[130:131], 0, v[4:5]
	global_load_dwordx4 v[80:83], v[4:5], off
	global_load_dwordx4 v[84:87], v[4:5], off offset:32
	global_load_dwordx4 v[88:91], v[4:5], off offset:64
	global_load_dwordx4 v[92:95], v[4:5], off offset:96
	ds_read_b128 v[4:7], v128
	ds_read_b128 v[8:11], v128 offset:32
	ds_read_b128 v[146:149], v128 offset:64
	ds_read_b128 v[150:153], v128 offset:96
	ds_read_b128 v[154:157], v128 offset:4608
	ds_read_b128 v[176:179], v128 offset:4640
	ds_read_b128 v[180:183], v128 offset:4672
	ds_read_b128 v[184:187], v128 offset:4704
	ds_read_b128 v[188:191], v128 offset:9216
	ds_read_b128 v[192:195], v128 offset:9248
	ds_read_b128 v[196:199], v128 offset:9280
	ds_read_b128 v[200:203], v128 offset:9312
	v_add_u32_e32 v163, 0x1200, v128
	s_waitcnt lgkmcnt(8)
	v_mfma_f32_32x32x16_bf16 v[64:79], v[4:7], v[0:3], 0
	v_mfma_f32_32x32x16_bf16 v[64:79], v[8:11], v[104:107], v[64:79]
	v_mfma_f32_32x32x16_bf16 v[64:79], v[146:149], v[100:103], v[64:79]
	v_mfma_f32_32x32x16_bf16 v[64:79], v[150:153], v[96:99], v[64:79]
	ds_read_b128 v[204:207], v128 offset:13824
	ds_read_b128 v[208:211], v128 offset:13856
	ds_read_b128 v[212:215], v128 offset:13888
	ds_read_b128 v[216:219], v128 offset:13920
	s_waitcnt lgkmcnt(8)
	v_mfma_f32_32x32x16_bf16 v[48:63], v[154:157], v[0:3], 0
	v_mfma_f32_32x32x16_bf16 v[48:63], v[176:179], v[104:107], v[48:63]
	v_mfma_f32_32x32x16_bf16 v[48:63], v[180:183], v[100:103], v[48:63]
	v_mfma_f32_32x32x16_bf16 v[48:63], v[184:187], v[96:99], v[48:63]
	ds_read_b128 v[220:223], v128 offset:18432
	ds_read_b128 v[224:227], v128 offset:18464
	ds_read_b128 v[228:231], v128 offset:18496
	ds_read_b128 v[232:235], v128 offset:18528
	s_waitcnt lgkmcnt(8)
	v_mfma_f32_32x32x16_bf16 v[32:47], v[188:191], v[0:3], 0
	v_mfma_f32_32x32x16_bf16 v[32:47], v[192:195], v[104:107], v[32:47]
	v_mfma_f32_32x32x16_bf16 v[32:47], v[196:199], v[100:103], v[32:47]
	v_mfma_f32_32x32x16_bf16 v[32:47], v[200:203], v[96:99], v[32:47]
	s_waitcnt lgkmcnt(4)
	v_mfma_f32_32x32x16_bf16 v[16:31], v[204:207], v[0:3], 0
	v_mfma_f32_32x32x16_bf16 v[16:31], v[208:211], v[104:107], v[16:31]
	v_mfma_f32_32x32x16_bf16 v[16:31], v[212:215], v[100:103], v[16:31]
	v_mfma_f32_32x32x16_bf16 v[16:31], v[216:219], v[96:99], v[16:31]
	s_waitcnt lgkmcnt(0)
	v_mfma_f32_32x32x16_bf16 v[0:15], v[220:223], v[0:3], 0
	v_mfma_f32_32x32x16_bf16 v[0:15], v[224:227], v[104:107], v[0:15]
	v_mfma_f32_32x32x16_bf16 v[0:15], v[228:231], v[100:103], v[0:15]
	v_mfma_f32_32x32x16_bf16 v[0:15], v[232:235], v[96:99], v[0:15]
	v_add_u32_e32 v96, s26, v109
	v_add_u32_e32 v96, 0x80, v96
	v_subrev_u32_e32 v171, 0x7f, v96
	v_mov_b32_e32 v172, 0x80
	v_cndmask_b32_e64 v171, v171, v172, s[46:47]
	v_add_u32_e32 v97, s26, v110
	v_sub_u32_e32 v102, v96, v97
	v_cvt_f32_u32_e32 v159, v102
	v_cmp_gt_u32_e32 vcc, v171, v102
	v_mul_f32_e32 v99, v129, v159
	v_fma_f32 v64, v64, v158, -v99
	v_add_u32_e32 v98, v96, v161
	v_add_u32_e32 v99, 32, v98
	v_cvt_f32_u32_e32 v159, v99
	v_cndmask_b32_e32 v64, v241, v64, vcc
	v_mul_f32_e32 v101, v129, v159
	v_cmp_gt_u32_e32 vcc, v171, v99
	v_fma_f32 v65, v65, v158, -v101
	v_add_u32_e32 v100, 2, v97
	v_sub_u32_e32 v101, v96, v100
	v_cvt_f32_u32_e32 v159, v101
	v_cndmask_b32_e32 v65, v241, v65, vcc
	v_cmp_gt_u32_e32 vcc, v171, v101
	v_mul_f32_e32 v101, v129, v159
	v_fma_f32 v66, v66, v158, -v101
	v_add_u32_e32 v100, 3, v97
	v_sub_u32_e32 v101, v96, v100
	v_cvt_f32_u32_e32 v159, v101
	v_cndmask_b32_e32 v66, v241, v66, vcc
	v_cmp_gt_u32_e32 vcc, v171, v101
	v_mul_f32_e32 v101, v129, v159
	v_fma_f32 v67, v67, v158, -v101
	v_add_u32_e32 v100, -8, v102
	v_cvt_f32_u32_e32 v159, v100
	v_cndmask_b32_e32 v67, v241, v67, vcc
	v_cmp_gt_u32_e32 vcc, v171, v100
	v_mul_f32_e32 v101, v129, v159
	v_fma_f32 v68, v68, v158, -v101
	v_add_u32_e32 v100, -9, v102
	v_cvt_f32_u32_e32 v159, v100
	v_cndmask_b32_e32 v68, v241, v68, vcc
	v_cmp_gt_u32_e32 vcc, v171, v100
	v_mul_f32_e32 v101, v129, v159
	v_fma_f32 v69, v69, v158, -v101
	v_add_u32_e32 v100, -10, v102
	v_cvt_f32_u32_e32 v159, v100
	v_cndmask_b32_e32 v69, v241, v69, vcc
	v_cmp_gt_u32_e32 vcc, v171, v100
	v_mul_f32_e32 v101, v129, v159
	v_fma_f32 v70, v70, v158, -v101
	v_add_u32_e32 v100, -11, v102
	v_cvt_f32_u32_e32 v159, v100
	v_cndmask_b32_e32 v70, v241, v70, vcc
	v_cmp_gt_u32_e32 vcc, v171, v100
	v_mul_f32_e32 v101, v129, v159
	v_fma_f32 v71, v71, v158, -v101
	v_add_u32_e32 v100, -16, v102
	v_cvt_f32_u32_e32 v159, v100
	v_cndmask_b32_e32 v71, v241, v71, vcc
	v_cmp_gt_u32_e32 vcc, v171, v100
	v_mul_f32_e32 v101, v129, v159
	v_fma_f32 v72, v72, v158, -v101
	v_subrev_u32_e32 v100, 17, v102
	v_cvt_f32_u32_e32 v159, v100
	v_cndmask_b32_e32 v72, v241, v72, vcc
	v_cmp_gt_u32_e32 vcc, v171, v100
	v_mul_f32_e32 v101, v129, v159
	v_fma_f32 v73, v73, v158, -v101
	v_subrev_u32_e32 v100, 18, v102
	v_cvt_f32_u32_e32 v159, v100
	v_cndmask_b32_e32 v73, v241, v73, vcc
	v_cmp_gt_u32_e32 vcc, v171, v100
	v_mul_f32_e32 v101, v129, v159
	v_fma_f32 v74, v74, v158, -v101
	v_subrev_u32_e32 v100, 19, v102
	v_cvt_f32_u32_e32 v159, v100
	v_cndmask_b32_e32 v74, v241, v74, vcc
	v_cmp_gt_u32_e32 vcc, v171, v100
	v_mul_f32_e32 v101, v129, v159
	v_fma_f32 v75, v75, v158, -v101
	v_subrev_u32_e32 v100, 24, v102
	v_cvt_f32_u32_e32 v159, v100
	v_cndmask_b32_e32 v75, v241, v75, vcc
	v_cmp_gt_u32_e32 vcc, v171, v100
	v_mul_f32_e32 v101, v129, v159
	v_fma_f32 v76, v76, v158, -v101
	v_subrev_u32_e32 v100, 25, v102
	v_cvt_f32_u32_e32 v159, v100
	v_cndmask_b32_e32 v76, v241, v76, vcc
	v_cmp_gt_u32_e32 vcc, v171, v100
	v_mul_f32_e32 v101, v129, v159
	v_fma_f32 v77, v77, v158, -v101
	v_subrev_u32_e32 v100, 26, v102
	v_cvt_f32_u32_e32 v159, v100
	v_cndmask_b32_e32 v77, v241, v77, vcc
	v_cmp_gt_u32_e32 vcc, v171, v100
	v_mul_f32_e32 v101, v129, v159
	v_fma_f32 v78, v78, v158, -v101
	v_subrev_u32_e32 v100, 27, v102
	v_cvt_f32_u32_e32 v159, v100
	v_add_u32_e32 v102, 32, v97
	v_sub_u32_e32 v103, v96, v102
	v_cndmask_b32_e32 v78, v241, v78, vcc
	v_cmp_gt_u32_e32 vcc, v171, v100
	v_mul_f32_e32 v101, v129, v159
	v_cvt_f32_u32_e32 v159, v103
	v_fma_f32 v79, v79, v158, -v101
	v_mul_f32_e32 v101, v129, v159
	v_cvt_f32_u32_e32 v159, v98
	v_fma_f32 v48, v48, v158, -v101
	v_mul_f32_e32 v101, v129, v159
	v_fma_f32 v49, v49, v158, -v101
	v_add_u32_e32 v100, 34, v97
	v_sub_u32_e32 v101, v96, v100
	v_cndmask_b32_e32 v79, v241, v79, vcc
	v_cmp_gt_u32_e32 vcc, v171, v103
	v_cvt_f32_u32_e32 v159, v101
	s_nop 0
	v_cndmask_b32_e32 v48, v241, v48, vcc
	v_cmp_gt_u32_e32 vcc, v171, v98
	s_nop 0
	s_nop 0
	v_cndmask_b32_e32 v49, v241, v49, vcc
	v_cmp_gt_u32_e32 vcc, v171, v101
	v_mul_f32_e32 v101, v129, v159
	v_fma_f32 v50, v50, v158, -v101
	v_add_u32_e32 v100, 35, v97
	v_sub_u32_e32 v101, v96, v100
	v_cvt_f32_u32_e32 v159, v101
	v_cndmask_b32_e32 v50, v241, v50, vcc
	v_cmp_gt_u32_e32 vcc, v171, v101
	v_mul_f32_e32 v101, v129, v159
	v_fma_f32 v51, v51, v158, -v101
	v_add_u32_e32 v100, -8, v103
	v_cvt_f32_u32_e32 v159, v100
	v_cndmask_b32_e32 v51, v241, v51, vcc
	v_cmp_gt_u32_e32 vcc, v171, v100
	v_mul_f32_e32 v101, v129, v159
	v_fma_f32 v52, v52, v158, -v101
	v_add_u32_e32 v100, -9, v103
	v_cvt_f32_u32_e32 v159, v100
	v_cndmask_b32_e32 v52, v241, v52, vcc
	v_cmp_gt_u32_e32 vcc, v171, v100
	v_mul_f32_e32 v101, v129, v159
	v_fma_f32 v53, v53, v158, -v101
	v_add_u32_e32 v100, -10, v103
	v_cvt_f32_u32_e32 v159, v100
	v_cndmask_b32_e32 v53, v241, v53, vcc
	v_cmp_gt_u32_e32 vcc, v171, v100
	v_mul_f32_e32 v101, v129, v159
	v_fma_f32 v54, v54, v158, -v101
	v_add_u32_e32 v100, -11, v103
	v_cvt_f32_u32_e32 v159, v100
	v_cndmask_b32_e32 v54, v241, v54, vcc
	v_cmp_gt_u32_e32 vcc, v171, v100
	v_mul_f32_e32 v101, v129, v159
	v_fma_f32 v55, v55, v158, -v101
	v_add_u32_e32 v100, -16, v103
	v_cvt_f32_u32_e32 v159, v100
	v_cndmask_b32_e32 v55, v241, v55, vcc
	v_cmp_gt_u32_e32 vcc, v171, v100
	v_mul_f32_e32 v101, v129, v159
	v_fma_f32 v56, v56, v158, -v101
	v_subrev_u32_e32 v100, 17, v103
	v_cvt_f32_u32_e32 v159, v100
	v_cndmask_b32_e32 v56, v241, v56, vcc
	v_cmp_gt_u32_e32 vcc, v171, v100
	v_mul_f32_e32 v101, v129, v159
	v_fma_f32 v57, v57, v158, -v101
	v_subrev_u32_e32 v100, 18, v103
	v_cvt_f32_u32_e32 v159, v100
	v_cndmask_b32_e32 v57, v241, v57, vcc
	v_cmp_gt_u32_e32 vcc, v171, v100
	v_mul_f32_e32 v101, v129, v159
	v_fma_f32 v58, v58, v158, -v101
	v_subrev_u32_e32 v100, 19, v103
	v_cvt_f32_u32_e32 v159, v100
	v_cndmask_b32_e32 v58, v241, v58, vcc
	v_cmp_gt_u32_e32 vcc, v171, v100
	v_mul_f32_e32 v101, v129, v159
	v_fma_f32 v59, v59, v158, -v101
	v_subrev_u32_e32 v100, 24, v103
	v_cvt_f32_u32_e32 v159, v100
	v_cndmask_b32_e32 v59, v241, v59, vcc
	v_cmp_gt_u32_e32 vcc, v171, v100
	v_mul_f32_e32 v101, v129, v159
	v_fma_f32 v60, v60, v158, -v101
	v_subrev_u32_e32 v100, 25, v103
	v_cvt_f32_u32_e32 v159, v100
	v_cndmask_b32_e32 v60, v241, v60, vcc
	v_cmp_gt_u32_e32 vcc, v171, v100
	v_mul_f32_e32 v101, v129, v159
	v_max3_f32 v99, v127, v64, v65
	v_fma_f32 v61, v61, v158, -v101
	v_subrev_u32_e32 v100, 26, v103
	v_cvt_f32_u32_e32 v159, v100
	v_max3_f32 v99, v99, v66, v67
	v_max3_f32 v99, v99, v68, v69
	v_max3_f32 v99, v99, v70, v71
	v_cndmask_b32_e32 v61, v241, v61, vcc
	v_cmp_gt_u32_e32 vcc, v171, v100
	v_mul_f32_e32 v101, v129, v159
	v_max3_f32 v99, v99, v72, v73
	v_fma_f32 v62, v62, v158, -v101
	v_subrev_u32_e32 v100, 27, v103
	v_max3_f32 v99, v99, v74, v75
	v_cvt_f32_u32_e32 v159, v100
	v_max3_f32 v99, v99, v76, v77
	v_max3_f32 v99, v99, v78, v79
	v_add_u32_e32 v146, 64, v97
	v_max3_f32 v99, v99, v48, v49
	v_sub_u32_e32 v147, v96, v146
	v_max3_f32 v99, v99, v50, v51
	v_cndmask_b32_e32 v62, v241, v62, vcc
	v_cmp_gt_u32_e32 vcc, v171, v100
	v_mul_f32_e32 v101, v129, v159
	v_cvt_f32_u32_e32 v159, v147
	v_max3_f32 v99, v99, v52, v53
	v_max3_f32 v99, v99, v54, v55
	v_max3_f32 v99, v99, v56, v57
	v_fma_f32 v63, v63, v158, -v101
	v_max3_f32 v99, v99, v58, v59
	v_cndmask_b32_e32 v63, v241, v63, vcc
	v_cmp_gt_u32_e32 vcc, v171, v147
	v_mul_f32_e32 v101, v129, v159
	v_max3_f32 v99, v99, v60, v61
	v_fma_f32 v32, v32, v158, -v101
	v_subrev_u32_e32 v161, 32, v161
	v_max3_f32 v102, v99, v62, v63
	v_cndmask_b32_e32 v99, v241, v32, vcc
	v_add_u32_e32 v32, v96, v161
	v_cvt_f32_u32_e32 v159, v32
	v_cmp_gt_u32_e32 vcc, v171, v32
	v_mul_f32_e32 v32, v129, v159
	v_fma_f32 v32, v33, v158, -v32
	v_cndmask_b32_e32 v100, v241, v32, vcc
	v_add_u32_e32 v32, 0x42, v97
	v_sub_u32_e32 v33, v96, v32
	v_cvt_f32_u32_e32 v159, v33
	v_cmp_gt_u32_e32 vcc, v171, v33
	v_mul_f32_e32 v33, v129, v159
	v_fma_f32 v32, v34, v158, -v33
	v_cndmask_b32_e32 v101, v241, v32, vcc
	v_add_u32_e32 v32, 0x43, v97
	v_sub_u32_e32 v33, v96, v32
	v_cvt_f32_u32_e32 v159, v33
	v_cmp_gt_u32_e32 vcc, v171, v33
	v_mul_f32_e32 v33, v129, v159
	v_fma_f32 v32, v35, v158, -v33
	v_max3_f32 v103, v102, v99, v100
	v_cndmask_b32_e32 v102, v241, v32, vcc
	v_add_u32_e32 v32, -8, v147
	v_cvt_f32_u32_e32 v159, v32
	v_cmp_gt_u32_e32 vcc, v171, v32
	v_mul_f32_e32 v33, v129, v159
	v_fma_f32 v32, v36, v158, -v33
	v_max3_f32 v34, v103, v101, v102
	v_cndmask_b32_e32 v103, v241, v32, vcc
	v_add_u32_e32 v32, -9, v147
	v_cvt_f32_u32_e32 v159, v32
	v_cmp_gt_u32_e32 vcc, v171, v32
	v_mul_f32_e32 v33, v129, v159
	v_fma_f32 v32, v37, v158, -v33
	v_cndmask_b32_e32 v104, v241, v32, vcc
	v_add_u32_e32 v32, -10, v147
	v_cvt_f32_u32_e32 v159, v32
	v_cmp_gt_u32_e32 vcc, v171, v32
	v_mul_f32_e32 v33, v129, v159
	v_fma_f32 v32, v38, v158, -v33
	v_cndmask_b32_e32 v105, v241, v32, vcc
	v_add_u32_e32 v32, -11, v147
	v_cvt_f32_u32_e32 v159, v32
	v_cmp_gt_u32_e32 vcc, v171, v32
	v_mul_f32_e32 v33, v129, v159
	v_fma_f32 v32, v39, v158, -v33
	v_cndmask_b32_e32 v106, v241, v32, vcc
	v_add_u32_e32 v32, -16, v147
	v_cvt_f32_u32_e32 v159, v32
	v_cmp_gt_u32_e32 vcc, v171, v32
	v_mul_f32_e32 v33, v129, v159
	v_fma_f32 v32, v40, v158, -v33
	v_cndmask_b32_e32 v107, v241, v32, vcc
	v_subrev_u32_e32 v32, 17, v147
	v_cvt_f32_u32_e32 v159, v32
	v_cmp_gt_u32_e32 vcc, v171, v32
	v_mul_f32_e32 v33, v129, v159
	v_fma_f32 v32, v41, v158, -v33
	v_cndmask_b32_e32 v164, v241, v32, vcc
	v_subrev_u32_e32 v32, 18, v147
	v_cvt_f32_u32_e32 v159, v32
	v_cmp_gt_u32_e32 vcc, v171, v32
	v_mul_f32_e32 v33, v129, v159
	v_fma_f32 v32, v42, v158, -v33
	v_cndmask_b32_e32 v165, v241, v32, vcc
	v_subrev_u32_e32 v32, 19, v147
	v_cvt_f32_u32_e32 v159, v32
	v_cmp_gt_u32_e32 vcc, v171, v32
	v_mul_f32_e32 v33, v129, v159
	v_fma_f32 v32, v43, v158, -v33
	v_cndmask_b32_e32 v166, v241, v32, vcc
	v_subrev_u32_e32 v32, 24, v147
	v_cvt_f32_u32_e32 v159, v32
	v_cmp_gt_u32_e32 vcc, v171, v32
	v_mul_f32_e32 v33, v129, v159
	v_fma_f32 v32, v44, v158, -v33
	v_cndmask_b32_e32 v167, v241, v32, vcc
	v_subrev_u32_e32 v32, 25, v147
	v_cvt_f32_u32_e32 v159, v32
	v_cmp_gt_u32_e32 vcc, v171, v32
	v_mul_f32_e32 v33, v129, v159
	v_fma_f32 v32, v45, v158, -v33
	v_cndmask_b32_e32 v168, v241, v32, vcc
	v_subrev_u32_e32 v32, 26, v147
	v_cvt_f32_u32_e32 v159, v32
	v_cmp_gt_u32_e32 vcc, v171, v32
	v_mul_f32_e32 v33, v129, v159
	v_fma_f32 v32, v46, v158, -v33
	v_cndmask_b32_e32 v169, v241, v32, vcc
	v_subrev_u32_e32 v32, 27, v147
	v_cvt_f32_u32_e32 v159, v32
	v_add_u32_e32 v35, 0x60, v97
	v_sub_u32_e32 v36, v96, v35
	v_cmp_gt_u32_e32 vcc, v171, v32
	v_mul_f32_e32 v33, v129, v159
	v_cvt_f32_u32_e32 v159, v36
	v_fma_f32 v32, v47, v158, -v33
	v_cndmask_b32_e32 v170, v241, v32, vcc
	v_mul_f32_e32 v33, v129, v159
	v_fma_f32 v16, v16, v158, -v33
	v_subrev_u32_e32 v32, 64, v98
	v_cvt_f32_u32_e32 v159, v32
	v_cmp_gt_u32_e32 vcc, v171, v36
	s_nop 0
	s_nop 0
	v_cndmask_b32_e32 v16, v241, v16, vcc
	v_cmp_gt_u32_e32 vcc, v171, v32
	v_mul_f32_e32 v33, v129, v159
	v_fma_f32 v17, v17, v158, -v33
	v_add_u32_e32 v32, 0x62, v97
	v_sub_u32_e32 v33, v96, v32
	v_cvt_f32_u32_e32 v159, v33
	v_cndmask_b32_e32 v17, v241, v17, vcc
	v_cmp_gt_u32_e32 vcc, v171, v33
	v_mul_f32_e32 v33, v129, v159
	v_fma_f32 v18, v18, v158, -v33
	v_add_u32_e32 v32, 0x63, v97
	v_sub_u32_e32 v33, v96, v32
	v_cvt_f32_u32_e32 v159, v33
	v_cndmask_b32_e32 v18, v241, v18, vcc
	v_cmp_gt_u32_e32 vcc, v171, v33
	v_mul_f32_e32 v33, v129, v159
	v_fma_f32 v19, v19, v158, -v33
	v_add_u32_e32 v32, -8, v36
	v_cvt_f32_u32_e32 v159, v32
	v_cndmask_b32_e32 v19, v241, v19, vcc
	v_cmp_gt_u32_e32 vcc, v171, v32
	v_mul_f32_e32 v33, v129, v159
	v_fma_f32 v20, v20, v158, -v33
	v_add_u32_e32 v32, -9, v36
	v_cvt_f32_u32_e32 v159, v32
	v_cndmask_b32_e32 v20, v241, v20, vcc
	v_cmp_gt_u32_e32 vcc, v171, v32
	v_mul_f32_e32 v33, v129, v159
	v_fma_f32 v21, v21, v158, -v33
	v_add_u32_e32 v32, -10, v36
	v_cvt_f32_u32_e32 v159, v32
	v_cndmask_b32_e32 v21, v241, v21, vcc
	v_cmp_gt_u32_e32 vcc, v171, v32
	v_mul_f32_e32 v33, v129, v159
	v_fma_f32 v22, v22, v158, -v33
	v_add_u32_e32 v32, -11, v36
	v_cvt_f32_u32_e32 v159, v32
	v_cndmask_b32_e32 v22, v241, v22, vcc
	v_cmp_gt_u32_e32 vcc, v171, v32
	v_mul_f32_e32 v33, v129, v159
	v_fma_f32 v23, v23, v158, -v33
	v_add_u32_e32 v32, -16, v36
	v_cvt_f32_u32_e32 v159, v32
	v_cndmask_b32_e32 v23, v241, v23, vcc
	v_cmp_gt_u32_e32 vcc, v171, v32
	v_mul_f32_e32 v33, v129, v159
	v_fma_f32 v24, v24, v158, -v33
	v_cndmask_b32_e32 v146, v241, v24, vcc
	v_subrev_u32_e32 v24, 17, v36
	v_cvt_f32_u32_e32 v159, v24
	v_cmp_gt_u32_e32 vcc, v171, v24
	v_mul_f32_e32 v24, v129, v159
	v_fma_f32 v24, v25, v158, -v24
	v_cndmask_b32_e32 v147, v241, v24, vcc
	v_subrev_u32_e32 v24, 18, v36
	v_cvt_f32_u32_e32 v159, v24
	v_cmp_gt_u32_e32 vcc, v171, v24
	v_mul_f32_e32 v25, v129, v159
	v_fma_f32 v24, v26, v158, -v25
	v_cndmask_b32_e32 v26, v241, v24, vcc
	v_subrev_u32_e32 v24, 19, v36
	v_cvt_f32_u32_e32 v159, v24
	v_cmp_gt_u32_e32 vcc, v171, v24
	v_mul_f32_e32 v25, v129, v159
	v_fma_f32 v24, v27, v158, -v25
	v_cndmask_b32_e32 v27, v241, v24, vcc
	v_subrev_u32_e32 v24, 24, v36
	v_cvt_f32_u32_e32 v159, v24
	v_cmp_gt_u32_e32 vcc, v171, v24
	v_mul_f32_e32 v25, v129, v159
	v_fma_f32 v24, v28, v158, -v25
	v_cndmask_b32_e32 v28, v241, v24, vcc
	v_subrev_u32_e32 v24, 25, v36
	v_cvt_f32_u32_e32 v159, v24
	v_cmp_gt_u32_e32 vcc, v171, v24
	v_mul_f32_e32 v25, v129, v159
	v_fma_f32 v24, v29, v158, -v25
	v_cndmask_b32_e32 v29, v241, v24, vcc
	v_subrev_u32_e32 v24, 26, v36
	v_max3_f32 v34, v34, v103, v104
	v_cvt_f32_u32_e32 v159, v24
	v_max3_f32 v34, v34, v105, v106
	v_max3_f32 v34, v34, v107, v164
	v_max3_f32 v34, v34, v165, v166
	v_max3_f32 v34, v34, v167, v168
	v_cmp_gt_u32_e32 vcc, v171, v24
	v_mul_f32_e32 v25, v129, v159
	v_max3_f32 v34, v34, v169, v170
	v_fma_f32 v24, v30, v158, -v25
	v_max3_f32 v34, v34, v16, v17
	v_cndmask_b32_e32 v30, v241, v24, vcc
	v_subrev_u32_e32 v24, 27, v36
	v_max3_f32 v34, v34, v18, v19
	v_cvt_f32_u32_e32 v159, v24
	v_max3_f32 v34, v34, v20, v21
	v_max3_f32 v34, v34, v22, v23
	v_add_u32_e32 v33, 0x80, v97
	v_max3_f32 v32, v34, v146, v147
	v_sub_u32_e32 v34, v96, v33
	v_cmp_gt_u32_e32 vcc, v171, v24
	v_mul_f32_e32 v25, v129, v159
	v_cvt_f32_u32_e32 v159, v34
	v_fma_f32 v24, v31, v158, -v25
	v_cndmask_b32_e32 v31, v241, v24, vcc
	v_cmp_gt_u32_e32 vcc, v171, v34
	v_mul_f32_e32 v25, v129, v159
	v_fma_f32 v0, v0, v158, -v25
	v_cndmask_b32_e32 v24, v241, v0, vcc
	v_add_u32_e32 v0, 0xffffffa0, v98
	v_cvt_f32_u32_e32 v159, v0
	v_cmp_gt_u32_e32 vcc, v171, v0
	v_mul_f32_e32 v0, v129, v159
	v_fma_f32 v0, v1, v158, -v0
	v_cndmask_b32_e32 v25, v241, v0, vcc
	v_add_u32_e32 v0, 0x82, v97
	v_sub_u32_e32 v1, v96, v0
	v_cvt_f32_u32_e32 v159, v1
	v_cmp_gt_u32_e32 vcc, v171, v1
	v_mul_f32_e32 v1, v129, v159
	v_fma_f32 v0, v2, v158, -v1
	v_cndmask_b32_e32 v98, v241, v0, vcc
	v_add_u32_e32 v0, 0x83, v97
	v_sub_u32_e32 v1, v96, v0
	v_cvt_f32_u32_e32 v159, v1
	v_cmp_gt_u32_e32 vcc, v171, v1
	v_mul_f32_e32 v1, v129, v159
	v_fma_f32 v0, v3, v158, -v1
	v_cndmask_b32_e32 v96, v241, v0, vcc
	v_add_u32_e32 v0, -8, v34
	v_cvt_f32_u32_e32 v159, v0
	v_cmp_gt_u32_e32 vcc, v171, v0
	v_mul_f32_e32 v1, v129, v159
	v_fma_f32 v0, v4, v158, -v1
	v_cndmask_b32_e32 v4, v241, v0, vcc
	v_add_u32_e32 v0, -9, v34
	v_cvt_f32_u32_e32 v159, v0
	v_cmp_gt_u32_e32 vcc, v171, v0
	v_mul_f32_e32 v1, v129, v159
	v_fma_f32 v0, v5, v158, -v1
	v_cndmask_b32_e32 v5, v241, v0, vcc
	v_add_u32_e32 v0, -10, v34
	v_cvt_f32_u32_e32 v159, v0
	v_cmp_gt_u32_e32 vcc, v171, v0
	v_mul_f32_e32 v1, v129, v159
	v_fma_f32 v0, v6, v158, -v1
	v_cndmask_b32_e32 v6, v241, v0, vcc
	v_add_u32_e32 v0, -11, v34
	v_cvt_f32_u32_e32 v159, v0
	v_cmp_gt_u32_e32 vcc, v171, v0
	v_mul_f32_e32 v1, v129, v159
	v_fma_f32 v0, v7, v158, -v1
	v_cndmask_b32_e32 v7, v241, v0, vcc
	v_add_u32_e32 v0, -16, v34
	v_cvt_f32_u32_e32 v159, v0
	v_cmp_gt_u32_e32 vcc, v171, v0
	v_mul_f32_e32 v1, v129, v159
	v_fma_f32 v0, v8, v158, -v1
	v_cndmask_b32_e32 v8, v241, v0, vcc
	v_subrev_u32_e32 v0, 17, v34
	v_cvt_f32_u32_e32 v159, v0
	v_cmp_gt_u32_e32 vcc, v171, v0
	v_mul_f32_e32 v1, v129, v159
	v_fma_f32 v0, v9, v158, -v1
	v_cndmask_b32_e32 v9, v241, v0, vcc
	v_subrev_u32_e32 v0, 18, v34
	v_cvt_f32_u32_e32 v159, v0
	v_cmp_gt_u32_e32 vcc, v171, v0
	v_mul_f32_e32 v1, v129, v159
	v_fma_f32 v0, v10, v158, -v1
	v_cndmask_b32_e32 v10, v241, v0, vcc
	v_subrev_u32_e32 v0, 19, v34
	v_cvt_f32_u32_e32 v159, v0
	v_cmp_gt_u32_e32 vcc, v171, v0
	v_mul_f32_e32 v1, v129, v159
	v_fma_f32 v0, v11, v158, -v1
	v_cndmask_b32_e32 v11, v241, v0, vcc
	v_subrev_u32_e32 v0, 24, v34
	v_cvt_f32_u32_e32 v159, v0
	v_cmp_gt_u32_e32 vcc, v171, v0
	v_mul_f32_e32 v1, v129, v159
	v_fma_f32 v0, v12, v158, -v1
	v_cndmask_b32_e32 v12, v241, v0, vcc
	v_subrev_u32_e32 v0, 25, v34
	v_cvt_f32_u32_e32 v159, v0
	v_cmp_gt_u32_e32 vcc, v171, v0
	v_mul_f32_e32 v1, v129, v159
	v_fma_f32 v0, v13, v158, -v1
	v_cndmask_b32_e32 v13, v241, v0, vcc
	v_subrev_u32_e32 v0, 26, v34
	v_cvt_f32_u32_e32 v159, v0
	v_max3_f32 v32, v32, v26, v27
	v_cmp_gt_u32_e32 vcc, v171, v0
	v_mul_f32_e32 v1, v129, v159
	v_max3_f32 v32, v32, v28, v29
	v_fma_f32 v0, v14, v158, -v1
	v_max3_f32 v32, v32, v30, v31
	v_cndmask_b32_e32 v14, v241, v0, vcc
	v_subrev_u32_e32 v0, 27, v34
	v_max3_f32 v32, v32, v24, v25
	v_cvt_f32_u32_e32 v159, v0
	v_max3_f32 v2, v32, v98, v96
	v_max3_f32 v2, v2, v4, v5
	v_max3_f32 v2, v2, v6, v7
	v_max3_f32 v2, v2, v8, v9
	v_cmp_gt_u32_e32 vcc, v171, v0
	v_mul_f32_e32 v1, v129, v159
	v_max3_f32 v2, v2, v10, v11
	v_fma_f32 v0, v15, v158, -v1
	v_max3_f32 v2, v2, v12, v13
	v_cndmask_b32_e32 v15, v241, v0, vcc
	v_max3_f32 v0, v2, v14, v15
	ds_bpermute_b32 v1, v123, v0
	s_cmpk_eq_i32 s27, 0x80
	v_mov_b32_e32 v128, v163
	s_waitcnt lgkmcnt(0)
	v_max_f32_e32 v1, v1, v1
	v_max_f32_e32 v97, v0, v1
	v_sub_f32_e32 v0, v64, v97
	v_mul_f32_e32 v0, 0x3fb8aa3b, v0
	v_sub_f32_e32 v2, v65, v97
	v_exp_f32_e32 v0, v0
	v_mul_f32_e32 v2, 0x3fb8aa3b, v2
	v_sub_f32_e32 v3, v66, v97
	v_exp_f32_e32 v2, v2
	v_mul_f32_e32 v3, 0x3fb8aa3b, v3
	v_sub_f32_e32 v32, v67, v97
	v_exp_f32_e32 v3, v3
	v_mul_f32_e32 v32, 0x3fb8aa3b, v32
	v_sub_f32_e32 v33, v68, v97
	v_exp_f32_e32 v32, v32
	v_mul_f32_e32 v33, 0x3fb8aa3b, v33
	v_sub_f32_e32 v34, v69, v97
	v_add_f32_e32 v1, 0, v0
	v_exp_f32_e32 v33, v33
	v_mul_f32_e32 v34, 0x3fb8aa3b, v34
	v_sub_f32_e32 v35, v70, v97
	v_add_f32_e32 v1, v2, v1
	v_exp_f32_e32 v34, v34
	v_mul_f32_e32 v35, 0x3fb8aa3b, v35
	v_sub_f32_e32 v36, v71, v97
	v_add_f32_e32 v1, v3, v1
	v_exp_f32_e32 v35, v35
	v_mul_f32_e32 v36, 0x3fb8aa3b, v36
	v_add_f32_e32 v1, v32, v1
	v_exp_f32_e32 v36, v36
	v_add_f32_e32 v1, v33, v1
	v_add_f32_e32 v1, v34, v1
	v_add_f32_e32 v1, v35, v1
	v_add_f32_e32 v37, v36, v1
	v_cvt_pk_bf16_f32 v1, v3, v32
	v_sub_f32_e32 v32, v72, v97
	v_mul_f32_e32 v32, 0x3fb8aa3b, v32
	v_exp_f32_e32 v32, v32
	v_cvt_pk_bf16_f32 v0, v0, v2
	v_cvt_pk_bf16_f32 v2, v33, v34
	v_sub_f32_e32 v34, v73, v97
	v_cvt_pk_bf16_f32 v3, v35, v36
	v_mul_f32_e32 v34, 0x3fb8aa3b, v34
	v_sub_f32_e32 v35, v74, v97
	v_exp_f32_e32 v34, v34
	v_mul_f32_e32 v35, 0x3fb8aa3b, v35
	v_sub_f32_e32 v36, v75, v97
	v_add_f32_e32 v33, v32, v37
	v_exp_f32_e32 v35, v35
	v_mul_f32_e32 v36, 0x3fb8aa3b, v36
	v_sub_f32_e32 v37, v76, v97
	v_exp_f32_e32 v36, v36
	v_mul_f32_e32 v37, 0x3fb8aa3b, v37
	v_sub_f32_e32 v38, v77, v97
	v_exp_f32_e32 v37, v37
	v_mul_f32_e32 v38, 0x3fb8aa3b, v38
	v_sub_f32_e32 v39, v78, v97
	v_add_f32_e32 v33, v34, v33
	v_exp_f32_e32 v38, v38
	v_mul_f32_e32 v39, 0x3fb8aa3b, v39
	v_sub_f32_e32 v40, v79, v97
	v_add_f32_e32 v33, v35, v33
	v_exp_f32_e32 v39, v39
	v_mul_f32_e32 v40, 0x3fb8aa3b, v40
	v_add_f32_e32 v33, v36, v33
	v_exp_f32_e32 v40, v40
	v_add_f32_e32 v33, v37, v33
	v_add_f32_e32 v33, v38, v33
	v_add_f32_e32 v33, v39, v33
	v_add_f32_e32 v41, v40, v33
	v_cvt_pk_bf16_f32 v33, v35, v36
	v_sub_f32_e32 v36, v48, v97
	v_mul_f32_e32 v36, 0x3fb8aa3b, v36
	v_exp_f32_e32 v36, v36
	v_cvt_pk_bf16_f32 v32, v32, v34
	v_cvt_pk_bf16_f32 v34, v37, v38
	v_sub_f32_e32 v38, v49, v97
	v_cvt_pk_bf16_f32 v35, v39, v40
	v_mul_f32_e32 v38, 0x3fb8aa3b, v38
	v_sub_f32_e32 v39, v50, v97
	v_exp_f32_e32 v38, v38
	v_mul_f32_e32 v39, 0x3fb8aa3b, v39
	v_sub_f32_e32 v40, v51, v97
	v_add_f32_e32 v37, v36, v41
	v_exp_f32_e32 v39, v39
	v_mul_f32_e32 v40, 0x3fb8aa3b, v40
	v_sub_f32_e32 v41, v52, v97
	v_exp_f32_e32 v40, v40
	v_mul_f32_e32 v41, 0x3fb8aa3b, v41
	v_sub_f32_e32 v42, v53, v97
	v_exp_f32_e32 v41, v41
	v_mul_f32_e32 v42, 0x3fb8aa3b, v42
	v_sub_f32_e32 v43, v54, v97
	v_add_f32_e32 v37, v38, v37
	v_exp_f32_e32 v42, v42
	v_mul_f32_e32 v43, 0x3fb8aa3b, v43
	v_sub_f32_e32 v44, v55, v97
	v_add_f32_e32 v37, v39, v37
	v_exp_f32_e32 v43, v43
	v_mul_f32_e32 v44, 0x3fb8aa3b, v44
	v_add_f32_e32 v37, v40, v37
	v_exp_f32_e32 v44, v44
	v_add_f32_e32 v37, v41, v37
	v_add_f32_e32 v37, v42, v37
	v_add_f32_e32 v37, v43, v37
	v_add_f32_e32 v45, v44, v37
	v_cvt_pk_bf16_f32 v37, v39, v40
	v_sub_f32_e32 v40, v56, v97
	v_mul_f32_e32 v40, 0x3fb8aa3b, v40
	v_exp_f32_e32 v40, v40
	v_cvt_pk_bf16_f32 v36, v36, v38
	v_cvt_pk_bf16_f32 v38, v41, v42
	v_sub_f32_e32 v42, v57, v97
	v_cvt_pk_bf16_f32 v39, v43, v44
	v_mul_f32_e32 v42, 0x3fb8aa3b, v42
	v_sub_f32_e32 v43, v58, v97
	v_exp_f32_e32 v42, v42
	v_mul_f32_e32 v43, 0x3fb8aa3b, v43
	v_sub_f32_e32 v44, v59, v97
	v_add_f32_e32 v41, v40, v45
	v_exp_f32_e32 v43, v43
	v_mul_f32_e32 v44, 0x3fb8aa3b, v44
	v_sub_f32_e32 v45, v60, v97
	v_exp_f32_e32 v44, v44
	v_mul_f32_e32 v45, 0x3fb8aa3b, v45
	v_sub_f32_e32 v46, v61, v97
	v_exp_f32_e32 v45, v45
	v_mul_f32_e32 v46, 0x3fb8aa3b, v46
	v_sub_f32_e32 v47, v62, v97
	v_add_f32_e32 v41, v42, v41
	v_exp_f32_e32 v46, v46
	v_mul_f32_e32 v47, 0x3fb8aa3b, v47
	v_sub_f32_e32 v48, v63, v97
	v_add_f32_e32 v41, v43, v41
	v_exp_f32_e32 v47, v47
	v_mul_f32_e32 v48, 0x3fb8aa3b, v48
	v_add_f32_e32 v41, v44, v41
	v_exp_f32_e32 v48, v48
	v_add_f32_e32 v41, v45, v41
	v_add_f32_e32 v41, v46, v41
	v_add_f32_e32 v41, v47, v41
	v_add_f32_e32 v49, v48, v41
	v_cvt_pk_bf16_f32 v41, v43, v44
	v_sub_f32_e32 v44, v99, v97
	v_mul_f32_e32 v44, 0x3fb8aa3b, v44
	v_exp_f32_e32 v44, v44
	v_cvt_pk_bf16_f32 v40, v40, v42
	v_cvt_pk_bf16_f32 v42, v45, v46
	v_sub_f32_e32 v46, v100, v97
	v_cvt_pk_bf16_f32 v43, v47, v48
	v_mul_f32_e32 v46, 0x3fb8aa3b, v46
	v_sub_f32_e32 v47, v101, v97
	v_exp_f32_e32 v46, v46
	v_mul_f32_e32 v47, 0x3fb8aa3b, v47
	v_sub_f32_e32 v48, v102, v97
	v_add_f32_e32 v45, v44, v49
	v_exp_f32_e32 v47, v47
	v_mul_f32_e32 v48, 0x3fb8aa3b, v48
	v_sub_f32_e32 v49, v103, v97
	v_exp_f32_e32 v48, v48
	v_mul_f32_e32 v49, 0x3fb8aa3b, v49
	v_sub_f32_e32 v50, v104, v97
	v_exp_f32_e32 v49, v49
	v_mul_f32_e32 v50, 0x3fb8aa3b, v50
	v_sub_f32_e32 v51, v105, v97
	v_add_f32_e32 v45, v46, v45
	v_exp_f32_e32 v50, v50
	v_mul_f32_e32 v51, 0x3fb8aa3b, v51
	v_sub_f32_e32 v52, v106, v97
	v_add_f32_e32 v45, v47, v45
	v_exp_f32_e32 v51, v51
	v_mul_f32_e32 v52, 0x3fb8aa3b, v52
	v_add_f32_e32 v45, v48, v45
	v_exp_f32_e32 v52, v52
	v_add_f32_e32 v45, v49, v45
	v_add_f32_e32 v45, v50, v45
	v_add_f32_e32 v45, v51, v45
	v_add_f32_e32 v53, v52, v45
	v_cvt_pk_bf16_f32 v45, v47, v48
	v_sub_f32_e32 v48, v107, v97
	v_mul_f32_e32 v48, 0x3fb8aa3b, v48
	v_exp_f32_e32 v48, v48
	v_cvt_pk_bf16_f32 v44, v44, v46
	v_cvt_pk_bf16_f32 v46, v49, v50
	v_sub_f32_e32 v50, v164, v97
	v_cvt_pk_bf16_f32 v47, v51, v52
	v_mul_f32_e32 v50, 0x3fb8aa3b, v50
	v_sub_f32_e32 v51, v165, v97
	v_exp_f32_e32 v50, v50
	v_mul_f32_e32 v51, 0x3fb8aa3b, v51
	v_sub_f32_e32 v52, v166, v97
	v_add_f32_e32 v49, v48, v53
	v_exp_f32_e32 v51, v51
	v_mul_f32_e32 v52, 0x3fb8aa3b, v52
	v_sub_f32_e32 v53, v167, v97
	v_exp_f32_e32 v52, v52
	v_mul_f32_e32 v53, 0x3fb8aa3b, v53
	v_sub_f32_e32 v54, v168, v97
	v_exp_f32_e32 v53, v53
	v_mul_f32_e32 v54, 0x3fb8aa3b, v54
	v_sub_f32_e32 v55, v169, v97
	v_add_f32_e32 v49, v50, v49
	v_exp_f32_e32 v54, v54
	v_mul_f32_e32 v55, 0x3fb8aa3b, v55
	v_sub_f32_e32 v56, v170, v97
	v_add_f32_e32 v49, v51, v49
	v_exp_f32_e32 v55, v55
	v_mul_f32_e32 v56, 0x3fb8aa3b, v56
	v_sub_f32_e32 v16, v16, v97
	v_add_f32_e32 v49, v52, v49
	v_exp_f32_e32 v56, v56
	v_mul_f32_e32 v16, 0x3fb8aa3b, v16
	v_sub_f32_e32 v17, v17, v97
	v_add_f32_e32 v49, v53, v49
	v_exp_f32_e32 v16, v16
	v_mul_f32_e32 v17, 0x3fb8aa3b, v17
	v_sub_f32_e32 v18, v18, v97
	v_add_f32_e32 v49, v54, v49
	v_exp_f32_e32 v17, v17
	v_mul_f32_e32 v18, 0x3fb8aa3b, v18
	v_sub_f32_e32 v19, v19, v97
	v_add_f32_e32 v49, v55, v49
	v_exp_f32_e32 v18, v18
	v_mul_f32_e32 v19, 0x3fb8aa3b, v19
	v_sub_f32_e32 v20, v20, v97
	v_add_f32_e32 v57, v56, v49
	v_exp_f32_e32 v19, v19
	v_mul_f32_e32 v20, 0x3fb8aa3b, v20
	v_sub_f32_e32 v21, v21, v97
	v_cvt_pk_bf16_f32 v49, v51, v52
	v_add_f32_e32 v52, v16, v57
	v_exp_f32_e32 v20, v20
	v_mul_f32_e32 v21, 0x3fb8aa3b, v21
	v_sub_f32_e32 v22, v22, v97
	v_add_f32_e32 v52, v17, v52
	v_exp_f32_e32 v21, v21
	v_mul_f32_e32 v22, 0x3fb8aa3b, v22
	v_sub_f32_e32 v23, v23, v97
	v_add_f32_e32 v52, v18, v52
	v_exp_f32_e32 v22, v22
	v_mul_f32_e32 v23, 0x3fb8aa3b, v23
	v_add_f32_e32 v52, v19, v52
	v_exp_f32_e32 v23, v23
	v_add_f32_e32 v52, v20, v52
	v_add_f32_e32 v52, v21, v52
	v_add_f32_e32 v52, v22, v52
	v_cvt_pk_bf16_f32 v51, v55, v56
	v_add_f32_e32 v56, v23, v52
	v_cvt_pk_bf16_f32 v52, v16, v17
	v_sub_f32_e32 v16, v146, v97
	v_cvt_pk_bf16_f32 v48, v48, v50
	v_cvt_pk_bf16_f32 v50, v53, v54
	v_cvt_pk_bf16_f32 v53, v18, v19
	v_mul_f32_e32 v16, 0x3fb8aa3b, v16
	v_sub_f32_e32 v18, v147, v97
	v_exp_f32_e32 v16, v16
	v_mul_f32_e32 v18, 0x3fb8aa3b, v18
	v_sub_f32_e32 v19, v26, v97
	v_cvt_pk_bf16_f32 v54, v20, v21
	v_exp_f32_e32 v18, v18
	v_mul_f32_e32 v19, 0x3fb8aa3b, v19
	v_sub_f32_e32 v20, v27, v97
	v_exp_f32_e32 v19, v19
	v_mul_f32_e32 v20, 0x3fb8aa3b, v20
	v_sub_f32_e32 v21, v28, v97
	v_cvt_pk_bf16_f32 v55, v22, v23
	v_exp_f32_e32 v20, v20
	v_mul_f32_e32 v21, 0x3fb8aa3b, v21
	v_sub_f32_e32 v22, v29, v97
	v_add_f32_e32 v17, v16, v56
	v_exp_f32_e32 v21, v21
	v_mul_f32_e32 v22, 0x3fb8aa3b, v22
	v_sub_f32_e32 v23, v30, v97
	v_add_f32_e32 v17, v18, v17
	v_exp_f32_e32 v22, v22
	v_mul_f32_e32 v23, 0x3fb8aa3b, v23
	v_sub_f32_e32 v26, v31, v97
	v_add_f32_e32 v17, v19, v17
	v_exp_f32_e32 v23, v23
	v_mul_f32_e32 v26, 0x3fb8aa3b, v26
	v_cvt_pk_bf16_f32 v56, v16, v18
	v_sub_f32_e32 v16, v24, v97
	v_add_f32_e32 v17, v20, v17
	v_exp_f32_e32 v26, v26
	v_mul_f32_e32 v16, 0x3fb8aa3b, v16
	v_sub_f32_e32 v18, v25, v97
	v_add_f32_e32 v17, v21, v17
	v_cvt_pk_bf16_f32 v57, v19, v20
	v_exp_f32_e32 v16, v16
	v_mul_f32_e32 v18, 0x3fb8aa3b, v18
	v_sub_f32_e32 v19, v98, v97
	v_add_f32_e32 v17, v22, v17
	v_exp_f32_e32 v18, v18
	v_mul_f32_e32 v19, 0x3fb8aa3b, v19
	v_sub_f32_e32 v20, v96, v97
	v_add_f32_e32 v17, v23, v17
	v_exp_f32_e32 v19, v19
	v_mul_f32_e32 v20, 0x3fb8aa3b, v20
	v_sub_f32_e32 v4, v4, v97
	v_add_f32_e32 v17, v26, v17
	v_exp_f32_e32 v20, v20
	v_mul_f32_e32 v4, 0x3fb8aa3b, v4
	v_sub_f32_e32 v5, v5, v97
	v_add_f32_e32 v17, v16, v17
	v_exp_f32_e32 v4, v4
	v_mul_f32_e32 v5, 0x3fb8aa3b, v5
	v_sub_f32_e32 v6, v6, v97
	v_sub_f32_e32 v7, v7, v97
	v_add_f32_e32 v17, v18, v17
	v_exp_f32_e32 v5, v5
	v_mul_f32_e32 v6, 0x3fb8aa3b, v6
	v_mul_f32_e32 v7, 0x3fb8aa3b, v7
	v_add_f32_e32 v17, v19, v17
	v_exp_f32_e32 v6, v6
	v_exp_f32_e32 v7, v7
	v_add_f32_e32 v17, v20, v17
	v_add_f32_e32 v17, v4, v17
	v_add_f32_e32 v17, v5, v17
	v_cvt_pk_bf16_f32 v62, v4, v5
	v_sub_f32_e32 v4, v8, v97
	v_add_f32_e32 v17, v6, v17
	v_cvt_pk_bf16_f32 v63, v6, v7
	v_mul_f32_e32 v4, 0x3fb8aa3b, v4
	v_sub_f32_e32 v6, v9, v97
	v_add_f32_e32 v17, v7, v17
	v_exp_f32_e32 v4, v4
	v_mul_f32_e32 v6, 0x3fb8aa3b, v6
	v_sub_f32_e32 v7, v10, v97
	v_exp_f32_e32 v6, v6
	v_mul_f32_e32 v7, 0x3fb8aa3b, v7
	v_sub_f32_e32 v8, v11, v97
	v_exp_f32_e32 v7, v7
	v_mul_f32_e32 v8, 0x3fb8aa3b, v8
	v_sub_f32_e32 v9, v12, v97
	v_exp_f32_e32 v8, v8
	v_mul_f32_e32 v9, 0x3fb8aa3b, v9
	v_sub_f32_e32 v10, v13, v97
	v_add_f32_e32 v5, v4, v17
	v_exp_f32_e32 v9, v9
	v_mul_f32_e32 v10, 0x3fb8aa3b, v10
	v_sub_f32_e32 v11, v14, v97
	v_add_f32_e32 v5, v6, v5
	v_exp_f32_e32 v10, v10
	v_mul_f32_e32 v11, 0x3fb8aa3b, v11
	v_sub_f32_e32 v12, v15, v97
	v_add_f32_e32 v5, v7, v5
	v_exp_f32_e32 v11, v11
	v_mul_f32_e32 v12, 0x3fb8aa3b, v12
	v_add_f32_e32 v5, v8, v5
	v_exp_f32_e32 v12, v12
	v_add_f32_e32 v5, v9, v5
	v_add_f32_e32 v5, v10, v5
	v_add_f32_e32 v5, v11, v5
	v_add_f32_e32 v5, v12, v5
	v_cvt_pk_bf16_f32 v64, v4, v6
	ds_bpermute_b32 v4, v123, v5
	v_cvt_pk_bf16_f32 v65, v7, v8
	v_cvt_pk_bf16_f32 v66, v9, v10
	v_cvt_pk_bf16_f32 v67, v11, v12
	v_add_u32_e32 v12, 0xffff9400, v162
	s_waitcnt lgkmcnt(0)
	v_add_f32_e32 v4, v5, v4
	v_sub_f32_e32 v5, v127, v97
	v_mul_f32_e32 v5, 0x3fb8aa3b, v5
	v_exp_f32_e32 v5, v5
	v_cvt_pk_bf16_f32 v58, v21, v22
	v_cvt_pk_bf16_f32 v59, v23, v26
	v_cvt_pk_bf16_f32 v60, v16, v18
	v_add_f32_e32 v69, v5, v4
	v_add_u32_e32 v173, 0xffff9400, v162
	ds_read_b64_tr_b16 v[176:177], v173
	ds_read_b64_tr_b16 v[178:179], v173 offset:1536
	ds_read_b64_tr_b16 v[180:181], v173 offset:64
	ds_read_b64_tr_b16 v[182:183], v173 offset:1600
	ds_read_b64_tr_b16 v[184:185], v173 offset:3072
	ds_read_b64_tr_b16 v[186:187], v173 offset:4608
	ds_read_b64_tr_b16 v[188:189], v173 offset:3136
	ds_read_b64_tr_b16 v[190:191], v173 offset:4672
	ds_read_b64_tr_b16 v[192:193], v173 offset:6144
	ds_read_b64_tr_b16 v[194:195], v173 offset:7680
	ds_read_b64_tr_b16 v[196:197], v173 offset:6208
	ds_read_b64_tr_b16 v[198:199], v173 offset:7744
	v_cvt_pk_bf16_f32 v61, v19, v20
	s_waitcnt lgkmcnt(8)
	v_mfma_f32_32x32x16_bf16 v[16:31], v[176:179], v[0:3], 0
	v_add_u32_e32 v68, s26, v160
	s_waitcnt vmcnt(2)
	v_mov_b64_e32 v[106:107], v[86:87]
	s_waitcnt vmcnt(1)
	v_mov_b64_e32 v[102:103], v[90:91]
	s_waitcnt vmcnt(0)
	v_mov_b64_e32 v[98:99], v[94:95]
	s_mov_b32 s26, s27
	v_mfma_f32_32x32x16_bf16 v[0:15], v[180:183], v[0:3], 0
	v_mov_b64_e32 v[104:105], v[84:85]
	v_mov_b64_e32 v[100:101], v[88:89]
	v_mov_b64_e32 v[96:97], v[92:93]
	ds_read_b64_tr_b16 v[200:201], v173 offset:9216
	ds_read_b64_tr_b16 v[202:203], v173 offset:10752
	ds_read_b64_tr_b16 v[204:205], v173 offset:9280
	ds_read_b64_tr_b16 v[206:207], v173 offset:10816
	s_waitcnt lgkmcnt(8)
	v_mfma_f32_32x32x16_bf16 v[0:15], v[188:191], v[32:35], v[0:15]
	v_mfma_f32_32x32x16_bf16 v[16:31], v[184:187], v[32:35], v[16:31]
	ds_read_b64_tr_b16 v[208:209], v173 offset:12288
	ds_read_b64_tr_b16 v[210:211], v173 offset:13824
	ds_read_b64_tr_b16 v[212:213], v173 offset:12352
	ds_read_b64_tr_b16 v[214:215], v173 offset:13888
	s_waitcnt lgkmcnt(8)
	v_mfma_f32_32x32x16_bf16 v[0:15], v[196:199], v[36:39], v[0:15]
	v_mfma_f32_32x32x16_bf16 v[16:31], v[192:195], v[36:39], v[16:31]
	ds_read_b64_tr_b16 v[216:217], v173 offset:15360
	ds_read_b64_tr_b16 v[218:219], v173 offset:16896
	ds_read_b64_tr_b16 v[220:221], v173 offset:15424
	ds_read_b64_tr_b16 v[222:223], v173 offset:16960
	s_waitcnt lgkmcnt(8)
	v_mfma_f32_32x32x16_bf16 v[0:15], v[204:207], v[40:43], v[0:15]
	v_mfma_f32_32x32x16_bf16 v[16:31], v[200:203], v[40:43], v[16:31]
	ds_read_b64_tr_b16 v[224:225], v173 offset:18432
	ds_read_b64_tr_b16 v[226:227], v173 offset:19968
	ds_read_b64_tr_b16 v[228:229], v173 offset:18496
	ds_read_b64_tr_b16 v[230:231], v173 offset:20032
	s_waitcnt lgkmcnt(8)
	v_mfma_f32_32x32x16_bf16 v[0:15], v[212:215], v[44:47], v[0:15]
	v_mfma_f32_32x32x16_bf16 v[16:31], v[208:211], v[44:47], v[16:31]
	ds_read_b64_tr_b16 v[232:233], v173 offset:21504
	ds_read_b64_tr_b16 v[234:235], v173 offset:23040
	ds_read_b64_tr_b16 v[236:237], v173 offset:21568
	ds_read_b64_tr_b16 v[238:239], v173 offset:23104
	s_waitcnt lgkmcnt(8)
	v_mfma_f32_32x32x16_bf16 v[0:15], v[220:223], v[48:51], v[0:15]
	v_mfma_f32_32x32x16_bf16 v[16:31], v[216:219], v[48:51], v[16:31]
	ds_read_b64_tr_b16 v[146:147], v173 offset:24576
	ds_read_b64_tr_b16 v[148:149], v173 offset:26112
	ds_read_b64_tr_b16 v[150:151], v173 offset:24640
	ds_read_b64_tr_b16 v[152:153], v173 offset:26176
	s_waitcnt lgkmcnt(8)
	v_mfma_f32_32x32x16_bf16 v[0:15], v[228:231], v[52:55], v[0:15]
	v_mfma_f32_32x32x16_bf16 v[16:31], v[224:227], v[52:55], v[16:31]
	ds_read_b64_tr_b16 v[70:71], v173 offset:27648
	ds_read_b64_tr_b16 v[72:73], v173 offset:29184
	ds_read_b64_tr_b16 v[74:75], v173 offset:27712
	ds_read_b64_tr_b16 v[76:77], v173 offset:29248
	s_waitcnt lgkmcnt(8)
	v_mfma_f32_32x32x16_bf16 v[0:15], v[236:239], v[56:59], v[0:15]
	v_mfma_f32_32x32x16_bf16 v[16:31], v[232:235], v[56:59], v[16:31]
	s_waitcnt lgkmcnt(4)
	v_mfma_f32_32x32x16_bf16 v[0:15], v[150:153], v[60:63], v[0:15]
	v_mfma_f32_32x32x16_bf16 v[16:31], v[146:149], v[60:63], v[16:31]
	v_add_u32_e32 v162, 0x1800, v162
	s_waitcnt lgkmcnt(0)
	v_mfma_f32_32x32x16_bf16 v[0:15], v[74:77], v[64:67], v[0:15]
	v_div_scale_f32 v32, s[44:45], v69, v69, 1.0
	v_rcp_f32_e32 v33, v32
	s_nop 0
	v_fma_f32 v34, -v32, v33, 1.0
	v_fmac_f32_e32 v33, v34, v33
	v_div_scale_f32 v34, vcc, 1.0, v69, 1.0
	v_mul_f32_e32 v35, v34, v33
	v_mfma_f32_32x32x16_bf16 v[16:31], v[70:73], v[64:67], v[16:31]
	v_fma_f32 v36, -v32, v35, v34
	v_fmac_f32_e32 v35, v36, v33
	v_fma_f32 v32, -v32, v35, v34
	v_div_fmas_f32 v32, v32, v33, v35
	v_div_fixup_f32 v34, v32, v69, 1.0
	v_ashrrev_i32_e32 v69, 31, v68
	v_mul_f32_e32 v0, v0, v34
	v_mul_f32_e32 v1, v1, v34
	v_lshlrev_b64 v[32:33], 11, v[68:69]
	v_cvt_pk_bf16_f32 v0, v0, v1
	v_mul_f32_e32 v1, v2, v34
	v_mul_f32_e32 v2, v3, v34
	v_lshl_add_u64 v[32:33], v[132:133], 0, v[32:33]
	v_cvt_pk_bf16_f32 v1, v1, v2
	global_store_dwordx2 v[32:33], v[0:1], off offset:64
	v_mul_f32_e32 v0, v20, v34
	v_mul_f32_e32 v1, v21, v34
	v_cvt_pk_bf16_f32 v0, v0, v1
	v_mul_f32_e32 v1, v22, v34
	v_mul_f32_e32 v2, v23, v34
	v_cvt_pk_bf16_f32 v1, v1, v2
	global_store_dwordx2 v[32:33], v[0:1], off offset:16
	v_mul_f32_e32 v0, v4, v34
	v_mul_f32_e32 v1, v5, v34
	v_cvt_pk_bf16_f32 v0, v0, v1
	v_mul_f32_e32 v1, v6, v34
	v_mul_f32_e32 v2, v7, v34
	v_cvt_pk_bf16_f32 v1, v1, v2
	global_store_dwordx2 v[32:33], v[0:1], off offset:80
	v_mul_f32_e32 v0, v24, v34
	v_mul_f32_e32 v1, v25, v34
	v_cvt_pk_bf16_f32 v0, v0, v1
	v_mul_f32_e32 v1, v26, v34
	v_mul_f32_e32 v2, v27, v34
	v_cvt_pk_bf16_f32 v1, v1, v2
	global_store_dwordx2 v[32:33], v[0:1], off offset:32
	v_mul_f32_e32 v0, v8, v34
	v_mul_f32_e32 v1, v9, v34
	v_cvt_pk_bf16_f32 v0, v0, v1
	v_mul_f32_e32 v1, v10, v34
	v_mul_f32_e32 v2, v11, v34
	v_cvt_pk_bf16_f32 v1, v1, v2
	global_store_dwordx2 v[32:33], v[0:1], off offset:96
	v_mul_f32_e32 v0, v28, v34
	v_mul_f32_e32 v1, v29, v34
	v_cvt_pk_bf16_f32 v0, v0, v1
	v_mul_f32_e32 v1, v30, v34
	v_mul_f32_e32 v2, v31, v34
	v_cvt_pk_bf16_f32 v1, v1, v2
	global_store_dwordx2 v[32:33], v[0:1], off offset:48
	v_mul_f32_e32 v0, v12, v34
	v_mul_f32_e32 v1, v13, v34
	v_cvt_pk_bf16_f32 v0, v0, v1
	v_mul_f32_e32 v1, v14, v34
	v_mul_f32_e32 v2, v15, v34
	v_mul_f32_e32 v16, v16, v34
	v_mul_f32_e32 v17, v17, v34
	v_cvt_pk_bf16_f32 v1, v1, v2
	v_cvt_pk_bf16_f32 v16, v16, v17
	v_mul_f32_e32 v17, v18, v34
	v_mul_f32_e32 v18, v19, v34
	global_store_dwordx2 v[32:33], v[0:1], off offset:112
	v_mov_b64_e32 v[0:1], v[80:81]
	v_cvt_pk_bf16_f32 v17, v17, v18
	v_mov_b64_e32 v[2:3], v[82:83]
	global_store_dwordx2 v[32:33], v[16:17], off
	s_cbranch_scc0 .LBB0_685
	s_add_i32 s15, s15, s74
	s_add_i32 s4, s4, s5
	s_cmpk_gt_i32 s15, 0xff
	s_barrier
	s_cbranch_scc0 .LBB0_684

.Lsm_qk:
	ds_read_b128 v[84:87], v32 offset:32
	ds_read_b128 v[88:91], v32 offset:48
	ds_read_b128 v[92:95], v33 offset:32
	ds_read_b128 v[96:99], v33 offset:48
	ds_read_b128 v[100:103], v34 offset:32
	ds_read_b128 v[104:107], v34 offset:48
	ds_read_b128 v[16:19], v15 offset:256
	ds_read_b128 v[20:23], v15 offset:272
	s_waitcnt lgkmcnt(8)
	v_fmac_f32_e32 v176, v60, v24
	v_fmac_f32_e32 v184, v68, v24
	v_fmac_f32_e32 v192, v76, v24
	v_fmac_f32_e32 v176, v61, v25
	v_fmac_f32_e32 v184, v69, v25
	v_fmac_f32_e32 v192, v77, v25
	v_fmac_f32_e32 v176, v62, v26
	v_fmac_f32_e32 v184, v70, v26
	v_fmac_f32_e32 v192, v78, v26
	v_fmac_f32_e32 v176, v63, v27
	v_fmac_f32_e32 v184, v71, v27
	v_fmac_f32_e32 v192, v79, v27
	v_fmac_f32_e32 v176, v64, v28
	v_fmac_f32_e32 v184, v72, v28
	v_fmac_f32_e32 v192, v80, v28
	v_fmac_f32_e32 v176, v65, v29
	v_fmac_f32_e32 v184, v73, v29
	v_fmac_f32_e32 v192, v81, v29
	v_fmac_f32_e32 v176, v66, v30
	v_fmac_f32_e32 v184, v74, v30
	v_fmac_f32_e32 v192, v82, v30
	v_fmac_f32_e32 v176, v67, v31
	v_fmac_f32_e32 v184, v75, v31
	v_fmac_f32_e32 v192, v83, v31
	ds_read_b128 v[24:27], v15 offset:512
	ds_read_b128 v[28:31], v15 offset:528
	s_waitcnt lgkmcnt(2)
	v_fmac_f32_e32 v177, v60, v16
	v_fmac_f32_e32 v185, v68, v16
	v_fmac_f32_e32 v193, v76, v16
	v_fmac_f32_e32 v177, v61, v17
	v_fmac_f32_e32 v185, v69, v17
	v_fmac_f32_e32 v193, v77, v17
	v_fmac_f32_e32 v177, v62, v18
	v_fmac_f32_e32 v185, v70, v18
	v_fmac_f32_e32 v193, v78, v18
	v_fmac_f32_e32 v177, v63, v19
	v_fmac_f32_e32 v185, v71, v19
	v_fmac_f32_e32 v193, v79, v19
	v_fmac_f32_e32 v177, v64, v20
	v_fmac_f32_e32 v185, v72, v20
	v_fmac_f32_e32 v193, v80, v20
	v_fmac_f32_e32 v177, v65, v21
	v_fmac_f32_e32 v185, v73, v21
	v_fmac_f32_e32 v193, v81, v21
	v_fmac_f32_e32 v177, v66, v22
	v_fmac_f32_e32 v185, v74, v22
	v_fmac_f32_e32 v193, v82, v22
	v_fmac_f32_e32 v177, v67, v23
	v_fmac_f32_e32 v185, v75, v23
	v_fmac_f32_e32 v193, v83, v23
	ds_read_b128 v[16:19], v15 offset:768
	ds_read_b128 v[20:23], v15 offset:784
	s_waitcnt lgkmcnt(2)
	v_fmac_f32_e32 v178, v60, v24
	v_fmac_f32_e32 v186, v68, v24
	v_fmac_f32_e32 v194, v76, v24
	v_fmac_f32_e32 v178, v61, v25
	v_fmac_f32_e32 v186, v69, v25
	v_fmac_f32_e32 v194, v77, v25
	v_fmac_f32_e32 v178, v62, v26
	v_fmac_f32_e32 v186, v70, v26
	v_fmac_f32_e32 v194, v78, v26
	v_fmac_f32_e32 v178, v63, v27
	v_fmac_f32_e32 v186, v71, v27
	v_fmac_f32_e32 v194, v79, v27
	v_fmac_f32_e32 v178, v64, v28
	v_fmac_f32_e32 v186, v72, v28
	v_fmac_f32_e32 v194, v80, v28
	v_fmac_f32_e32 v178, v65, v29
	v_fmac_f32_e32 v186, v73, v29
	v_fmac_f32_e32 v194, v81, v29
	v_fmac_f32_e32 v178, v66, v30
	v_fmac_f32_e32 v186, v74, v30
	v_fmac_f32_e32 v194, v82, v30
	v_fmac_f32_e32 v178, v67, v31
	v_fmac_f32_e32 v186, v75, v31
	v_fmac_f32_e32 v194, v83, v31
	ds_read_b128 v[24:27], v15 offset:1024
	ds_read_b128 v[28:31], v15 offset:1040
	s_waitcnt lgkmcnt(2)
	v_fmac_f32_e32 v179, v60, v16
	v_fmac_f32_e32 v187, v68, v16
	v_fmac_f32_e32 v195, v76, v16
	v_fmac_f32_e32 v179, v61, v17
	v_fmac_f32_e32 v187, v69, v17
	v_fmac_f32_e32 v195, v77, v17
	v_fmac_f32_e32 v179, v62, v18
	v_fmac_f32_e32 v187, v70, v18
	v_fmac_f32_e32 v195, v78, v18
	v_fmac_f32_e32 v179, v63, v19
	v_fmac_f32_e32 v187, v71, v19
	v_fmac_f32_e32 v195, v79, v19
	v_fmac_f32_e32 v179, v64, v20
	v_fmac_f32_e32 v187, v72, v20
	v_fmac_f32_e32 v195, v80, v20
	v_fmac_f32_e32 v179, v65, v21
	v_fmac_f32_e32 v187, v73, v21
	v_fmac_f32_e32 v195, v81, v21
	v_fmac_f32_e32 v179, v66, v22
	v_fmac_f32_e32 v187, v74, v22
	v_fmac_f32_e32 v195, v82, v22
	v_fmac_f32_e32 v179, v67, v23
	v_fmac_f32_e32 v187, v75, v23
	v_fmac_f32_e32 v195, v83, v23
	ds_read_b128 v[16:19], v15 offset:1280
	ds_read_b128 v[20:23], v15 offset:1296
	s_waitcnt lgkmcnt(2)
	v_fmac_f32_e32 v180, v60, v24
	v_fmac_f32_e32 v188, v68, v24
	v_fmac_f32_e32 v196, v76, v24
	v_fmac_f32_e32 v180, v61, v25
	v_fmac_f32_e32 v188, v69, v25
	v_fmac_f32_e32 v196, v77, v25
	v_fmac_f32_e32 v180, v62, v26
	v_fmac_f32_e32 v188, v70, v26
	v_fmac_f32_e32 v196, v78, v26
	v_fmac_f32_e32 v180, v63, v27
	v_fmac_f32_e32 v188, v71, v27
	v_fmac_f32_e32 v196, v79, v27
	v_fmac_f32_e32 v180, v64, v28
	v_fmac_f32_e32 v188, v72, v28
	v_fmac_f32_e32 v196, v80, v28
	v_fmac_f32_e32 v180, v65, v29
	v_fmac_f32_e32 v188, v73, v29
	v_fmac_f32_e32 v196, v81, v29
	v_fmac_f32_e32 v180, v66, v30
	v_fmac_f32_e32 v188, v74, v30
	v_fmac_f32_e32 v196, v82, v30
	v_fmac_f32_e32 v180, v67, v31
	v_fmac_f32_e32 v188, v75, v31
	v_fmac_f32_e32 v196, v83, v31
	ds_read_b128 v[24:27], v15 offset:1536
	ds_read_b128 v[28:31], v15 offset:1552
	s_waitcnt lgkmcnt(2)
	v_fmac_f32_e32 v181, v60, v16
	v_fmac_f32_e32 v189, v68, v16
	v_fmac_f32_e32 v197, v76, v16
	v_fmac_f32_e32 v181, v61, v17
	v_fmac_f32_e32 v189, v69, v17
	v_fmac_f32_e32 v197, v77, v17
	v_fmac_f32_e32 v181, v62, v18
	v_fmac_f32_e32 v189, v70, v18
	v_fmac_f32_e32 v197, v78, v18
	v_fmac_f32_e32 v181, v63, v19
	v_fmac_f32_e32 v189, v71, v19
	v_fmac_f32_e32 v197, v79, v19
	v_fmac_f32_e32 v181, v64, v20
	v_fmac_f32_e32 v189, v72, v20
	v_fmac_f32_e32 v197, v80, v20
	v_fmac_f32_e32 v181, v65, v21
	v_fmac_f32_e32 v189, v73, v21
	v_fmac_f32_e32 v197, v81, v21
	v_fmac_f32_e32 v181, v66, v22
	v_fmac_f32_e32 v189, v74, v22
	v_fmac_f32_e32 v197, v82, v22
	v_fmac_f32_e32 v181, v67, v23
	v_fmac_f32_e32 v189, v75, v23
	v_fmac_f32_e32 v197, v83, v23
	ds_read_b128 v[16:19], v15 offset:1792
	ds_read_b128 v[20:23], v15 offset:1808
	s_waitcnt lgkmcnt(2)
	v_fmac_f32_e32 v182, v60, v24
	v_fmac_f32_e32 v190, v68, v24
	v_fmac_f32_e32 v198, v76, v24
	v_fmac_f32_e32 v182, v61, v25
	v_fmac_f32_e32 v190, v69, v25
	v_fmac_f32_e32 v198, v77, v25
	v_fmac_f32_e32 v182, v62, v26
	v_fmac_f32_e32 v190, v70, v26
	v_fmac_f32_e32 v198, v78, v26
	v_fmac_f32_e32 v182, v63, v27
	v_fmac_f32_e32 v190, v71, v27
	v_fmac_f32_e32 v198, v79, v27
	v_fmac_f32_e32 v182, v64, v28
	v_fmac_f32_e32 v190, v72, v28
	v_fmac_f32_e32 v198, v80, v28
	v_fmac_f32_e32 v182, v65, v29
	v_fmac_f32_e32 v190, v73, v29
	v_fmac_f32_e32 v198, v81, v29
	v_fmac_f32_e32 v182, v66, v30
	v_fmac_f32_e32 v190, v74, v30
	v_fmac_f32_e32 v198, v82, v30
	v_fmac_f32_e32 v182, v67, v31
	v_fmac_f32_e32 v190, v75, v31
	v_fmac_f32_e32 v198, v83, v31
	ds_read_b128 v[24:27], v15 offset:32
	ds_read_b128 v[28:31], v15 offset:48
	s_waitcnt lgkmcnt(2)
	v_fmac_f32_e32 v183, v60, v16
	v_fmac_f32_e32 v191, v68, v16
	v_fmac_f32_e32 v199, v76, v16
	v_fmac_f32_e32 v183, v61, v17
	v_fmac_f32_e32 v191, v69, v17
	v_fmac_f32_e32 v199, v77, v17
	v_fmac_f32_e32 v183, v62, v18
	v_fmac_f32_e32 v191, v70, v18
	v_fmac_f32_e32 v199, v78, v18
	v_fmac_f32_e32 v183, v63, v19
	v_fmac_f32_e32 v191, v71, v19
	v_fmac_f32_e32 v199, v79, v19
	v_fmac_f32_e32 v183, v64, v20
	v_fmac_f32_e32 v191, v72, v20
	v_fmac_f32_e32 v199, v80, v20
	v_fmac_f32_e32 v183, v65, v21
	v_fmac_f32_e32 v191, v73, v21
	v_fmac_f32_e32 v199, v81, v21
	v_fmac_f32_e32 v183, v66, v22
	v_fmac_f32_e32 v191, v74, v22
	v_fmac_f32_e32 v199, v82, v22
	v_fmac_f32_e32 v183, v67, v23
	v_fmac_f32_e32 v191, v75, v23
	v_fmac_f32_e32 v199, v83, v23
	ds_read_b128 v[60:63], v32 offset:64
	ds_read_b128 v[64:67], v32 offset:80
	ds_read_b128 v[68:71], v33 offset:64
	ds_read_b128 v[72:75], v33 offset:80
	ds_read_b128 v[76:79], v34 offset:64
	ds_read_b128 v[80:83], v34 offset:80
	ds_read_b128 v[16:19], v15 offset:288
	ds_read_b128 v[20:23], v15 offset:304
	s_waitcnt lgkmcnt(8)
	v_fmac_f32_e32 v176, v84, v24
	v_fmac_f32_e32 v184, v92, v24
	v_fmac_f32_e32 v192, v100, v24
	v_fmac_f32_e32 v176, v85, v25
	v_fmac_f32_e32 v184, v93, v25
	v_fmac_f32_e32 v192, v101, v25
	v_fmac_f32_e32 v176, v86, v26
	v_fmac_f32_e32 v184, v94, v26
	v_fmac_f32_e32 v192, v102, v26
	v_fmac_f32_e32 v176, v87, v27
	v_fmac_f32_e32 v184, v95, v27
	v_fmac_f32_e32 v192, v103, v27
	v_fmac_f32_e32 v176, v88, v28
	v_fmac_f32_e32 v184, v96, v28
	v_fmac_f32_e32 v192, v104, v28
	v_fmac_f32_e32 v176, v89, v29
	v_fmac_f32_e32 v184, v97, v29
	v_fmac_f32_e32 v192, v105, v29
	v_fmac_f32_e32 v176, v90, v30
	v_fmac_f32_e32 v184, v98, v30
	v_fmac_f32_e32 v192, v106, v30
	v_fmac_f32_e32 v176, v91, v31
	v_fmac_f32_e32 v184, v99, v31
	v_fmac_f32_e32 v192, v107, v31
	ds_read_b128 v[24:27], v15 offset:544
	ds_read_b128 v[28:31], v15 offset:560
	s_waitcnt lgkmcnt(2)
	v_fmac_f32_e32 v177, v84, v16
	v_fmac_f32_e32 v185, v92, v16
	v_fmac_f32_e32 v193, v100, v16
	v_fmac_f32_e32 v177, v85, v17
	v_fmac_f32_e32 v185, v93, v17
	v_fmac_f32_e32 v193, v101, v17
	v_fmac_f32_e32 v177, v86, v18
	v_fmac_f32_e32 v185, v94, v18
	v_fmac_f32_e32 v193, v102, v18
	v_fmac_f32_e32 v177, v87, v19
	v_fmac_f32_e32 v185, v95, v19
	v_fmac_f32_e32 v193, v103, v19
	v_fmac_f32_e32 v177, v88, v20
	v_fmac_f32_e32 v185, v96, v20
	v_fmac_f32_e32 v193, v104, v20
	v_fmac_f32_e32 v177, v89, v21
	v_fmac_f32_e32 v185, v97, v21
	v_fmac_f32_e32 v193, v105, v21
	v_fmac_f32_e32 v177, v90, v22
	v_fmac_f32_e32 v185, v98, v22
	v_fmac_f32_e32 v193, v106, v22
	v_fmac_f32_e32 v177, v91, v23
	v_fmac_f32_e32 v185, v99, v23
	v_fmac_f32_e32 v193, v107, v23
	ds_read_b128 v[16:19], v15 offset:800
	ds_read_b128 v[20:23], v15 offset:816
	s_waitcnt lgkmcnt(2)
	v_fmac_f32_e32 v178, v84, v24
	v_fmac_f32_e32 v186, v92, v24
	v_fmac_f32_e32 v194, v100, v24
	v_fmac_f32_e32 v178, v85, v25
	v_fmac_f32_e32 v186, v93, v25
	v_fmac_f32_e32 v194, v101, v25
	v_fmac_f32_e32 v178, v86, v26
	v_fmac_f32_e32 v186, v94, v26
	v_fmac_f32_e32 v194, v102, v26
	v_fmac_f32_e32 v178, v87, v27
	v_fmac_f32_e32 v186, v95, v27
	v_fmac_f32_e32 v194, v103, v27
	v_fmac_f32_e32 v178, v88, v28
	v_fmac_f32_e32 v186, v96, v28
	v_fmac_f32_e32 v194, v104, v28
	v_fmac_f32_e32 v178, v89, v29
	v_fmac_f32_e32 v186, v97, v29
	v_fmac_f32_e32 v194, v105, v29
	v_fmac_f32_e32 v178, v90, v30
	v_fmac_f32_e32 v186, v98, v30
	v_fmac_f32_e32 v194, v106, v30
	v_fmac_f32_e32 v178, v91, v31
	v_fmac_f32_e32 v186, v99, v31
	v_fmac_f32_e32 v194, v107, v31
	ds_read_b128 v[24:27], v15 offset:1056
	ds_read_b128 v[28:31], v15 offset:1072
	s_waitcnt lgkmcnt(2)
	v_fmac_f32_e32 v179, v84, v16
	v_fmac_f32_e32 v187, v92, v16
	v_fmac_f32_e32 v195, v100, v16
	v_fmac_f32_e32 v179, v85, v17
	v_fmac_f32_e32 v187, v93, v17
	v_fmac_f32_e32 v195, v101, v17
	v_fmac_f32_e32 v179, v86, v18
	v_fmac_f32_e32 v187, v94, v18
	v_fmac_f32_e32 v195, v102, v18
	v_fmac_f32_e32 v179, v87, v19
	v_fmac_f32_e32 v187, v95, v19
	v_fmac_f32_e32 v195, v103, v19
	v_fmac_f32_e32 v179, v88, v20
	v_fmac_f32_e32 v187, v96, v20
	v_fmac_f32_e32 v195, v104, v20
	v_fmac_f32_e32 v179, v89, v21
	v_fmac_f32_e32 v187, v97, v21
	v_fmac_f32_e32 v195, v105, v21
	v_fmac_f32_e32 v179, v90, v22
	v_fmac_f32_e32 v187, v98, v22
	v_fmac_f32_e32 v195, v106, v22
	v_fmac_f32_e32 v179, v91, v23
	v_fmac_f32_e32 v187, v99, v23
	v_fmac_f32_e32 v195, v107, v23
	ds_read_b128 v[16:19], v15 offset:1312
	ds_read_b128 v[20:23], v15 offset:1328
	s_waitcnt lgkmcnt(2)
	v_fmac_f32_e32 v180, v84, v24
	v_fmac_f32_e32 v188, v92, v24
	v_fmac_f32_e32 v196, v100, v24
	v_fmac_f32_e32 v180, v85, v25
	v_fmac_f32_e32 v188, v93, v25
	v_fmac_f32_e32 v196, v101, v25
	v_fmac_f32_e32 v180, v86, v26
	v_fmac_f32_e32 v188, v94, v26
	v_fmac_f32_e32 v196, v102, v26
	v_fmac_f32_e32 v180, v87, v27
	v_fmac_f32_e32 v188, v95, v27
	v_fmac_f32_e32 v196, v103, v27
	v_fmac_f32_e32 v180, v88, v28
	v_fmac_f32_e32 v188, v96, v28
	v_fmac_f32_e32 v196, v104, v28
	v_fmac_f32_e32 v180, v89, v29
	v_fmac_f32_e32 v188, v97, v29
	v_fmac_f32_e32 v196, v105, v29
	v_fmac_f32_e32 v180, v90, v30
	v_fmac_f32_e32 v188, v98, v30
	v_fmac_f32_e32 v196, v106, v30
	v_fmac_f32_e32 v180, v91, v31
	v_fmac_f32_e32 v188, v99, v31
	v_fmac_f32_e32 v196, v107, v31
	ds_read_b128 v[24:27], v15 offset:1568
	ds_read_b128 v[28:31], v15 offset:1584
	s_waitcnt lgkmcnt(2)
	v_fmac_f32_e32 v181, v84, v16
	v_fmac_f32_e32 v189, v92, v16
	v_fmac_f32_e32 v197, v100, v16
	v_fmac_f32_e32 v181, v85, v17
	v_fmac_f32_e32 v189, v93, v17
	v_fmac_f32_e32 v197, v101, v17
	v_fmac_f32_e32 v181, v86, v18
	v_fmac_f32_e32 v189, v94, v18
	v_fmac_f32_e32 v197, v102, v18
	v_fmac_f32_e32 v181, v87, v19
	v_fmac_f32_e32 v189, v95, v19
	v_fmac_f32_e32 v197, v103, v19
	v_fmac_f32_e32 v181, v88, v20
	v_fmac_f32_e32 v189, v96, v20
	v_fmac_f32_e32 v197, v104, v20
	v_fmac_f32_e32 v181, v89, v21
	v_fmac_f32_e32 v189, v97, v21
	v_fmac_f32_e32 v197, v105, v21
	v_fmac_f32_e32 v181, v90, v22
	v_fmac_f32_e32 v189, v98, v22
	v_fmac_f32_e32 v197, v106, v22
	v_fmac_f32_e32 v181, v91, v23
	v_fmac_f32_e32 v189, v99, v23
	v_fmac_f32_e32 v197, v107, v23
	ds_read_b128 v[16:19], v15 offset:1824
	ds_read_b128 v[20:23], v15 offset:1840
	s_waitcnt lgkmcnt(2)
	v_fmac_f32_e32 v182, v84, v24
	v_fmac_f32_e32 v190, v92, v24
	v_fmac_f32_e32 v198, v100, v24
	v_fmac_f32_e32 v182, v85, v25
	v_fmac_f32_e32 v190, v93, v25
	v_fmac_f32_e32 v198, v101, v25
	v_fmac_f32_e32 v182, v86, v26
	v_fmac_f32_e32 v190, v94, v26
	v_fmac_f32_e32 v198, v102, v26
	v_fmac_f32_e32 v182, v87, v27
	v_fmac_f32_e32 v190, v95, v27
	v_fmac_f32_e32 v198, v103, v27
	v_fmac_f32_e32 v182, v88, v28
	v_fmac_f32_e32 v190, v96, v28
	v_fmac_f32_e32 v198, v104, v28
	v_fmac_f32_e32 v182, v89, v29
	v_fmac_f32_e32 v190, v97, v29
	v_fmac_f32_e32 v198, v105, v29
	v_fmac_f32_e32 v182, v90, v30
	v_fmac_f32_e32 v190, v98, v30
	v_fmac_f32_e32 v198, v106, v30
	v_fmac_f32_e32 v182, v91, v31
	v_fmac_f32_e32 v190, v99, v31
	v_fmac_f32_e32 v198, v107, v31
	ds_read_b128 v[24:27], v15 offset:64
	ds_read_b128 v[28:31], v15 offset:80
	s_waitcnt lgkmcnt(2)
	v_fmac_f32_e32 v183, v84, v16
	v_fmac_f32_e32 v191, v92, v16
	v_fmac_f32_e32 v199, v100, v16
	v_fmac_f32_e32 v183, v85, v17
	v_fmac_f32_e32 v191, v93, v17
	v_fmac_f32_e32 v199, v101, v17
	v_fmac_f32_e32 v183, v86, v18
	v_fmac_f32_e32 v191, v94, v18
	v_fmac_f32_e32 v199, v102, v18
	v_fmac_f32_e32 v183, v87, v19
	v_fmac_f32_e32 v191, v95, v19
	v_fmac_f32_e32 v199, v103, v19
	v_fmac_f32_e32 v183, v88, v20
	v_fmac_f32_e32 v191, v96, v20
	v_fmac_f32_e32 v199, v104, v20
	v_fmac_f32_e32 v183, v89, v21
	v_fmac_f32_e32 v191, v97, v21
	v_fmac_f32_e32 v199, v105, v21
	v_fmac_f32_e32 v183, v90, v22
	v_fmac_f32_e32 v191, v98, v22
	v_fmac_f32_e32 v199, v106, v22
	v_fmac_f32_e32 v183, v91, v23
	v_fmac_f32_e32 v191, v99, v23
	v_fmac_f32_e32 v199, v107, v23
	v_add_u32_e32 v32, 64, v32
	v_add_u32_e32 v33, 64, v33
	v_add_u32_e32 v34, 64, v34
	v_add_u32_e32 v15, 64, v15
	s_add_i32 s17, s17, 1
	s_cmp_lt_u32 s17, 4
	s_cbranch_scc1 .Lsm_qk
	s_waitcnt lgkmcnt(0)
	v_sub_u32_e32 v10, s3, v108
	v_add_u32_e32 v38, 0, v10
	v_cvt_f32_i32_e32 v39, v38
	v_cmp_gt_u32_e32 vcc, s3, v38
	v_mul_f32_e32 v39, v14, v39
	v_fma_f32 v176, v176, s52, -v39
	v_cndmask_b32_e32 v176, v241, v176, vcc
	v_add_u32_e32 v38, 0xffffffc0, v10
	v_cvt_f32_i32_e32 v39, v38
	v_cmp_gt_u32_e32 vcc, s3, v38
	v_mul_f32_e32 v39, v14, v39
	v_fma_f32 v184, v184, s52, -v39
	v_cndmask_b32_e32 v184, v241, v184, vcc
	v_add_u32_e32 v38, 0xffffff80, v10
	v_cvt_f32_i32_e32 v39, v38
	v_cmp_gt_u32_e32 vcc, s3, v38
	v_mul_f32_e32 v39, v14, v39
	v_fma_f32 v192, v192, s52, -v39
	s_and_b64 vcc, s[40:41], vcc
	v_cndmask_b32_e32 v192, v241, v192, vcc
	v_max3_f32 v40, v176, v184, v192
	v_mov_b32_e32 v41, v241
	s_nop 1
	v_mov_b32_dpp v41, v40 quad_perm:[1,0,3,2] row_mask:0xf bank_mask:0xf
	v_max_f32_e32 v40, v40, v41
	v_mov_b32_e32 v41, v241
	s_nop 1
	v_mov_b32_dpp v41, v40 quad_perm:[2,3,0,1] row_mask:0xf bank_mask:0xf
	v_max_f32_e32 v40, v40, v41
	v_mov_b32_e32 v41, v241
	s_nop 1
	v_mov_b32_dpp v41, v40 row_half_mirror row_mask:0xf bank_mask:0xf
	v_max_f32_e32 v40, v40, v41
	v_mov_b32_e32 v41, v241
	s_nop 1
	v_mov_b32_dpp v41, v40 row_mirror row_mask:0xf bank_mask:0xf
	v_max_f32_e32 v40, v40, v41
	v_mov_b32_e32 v41, v241
	s_nop 1
	v_mov_b32_dpp v41, v40 row_bcast:15 row_mask:0xa bank_mask:0xf
	v_max_f32_e32 v40, v40, v41
	v_mov_b32_e32 v41, v241
	s_nop 1
	v_mov_b32_dpp v41, v40 row_bcast:31 row_mask:0xc bank_mask:0xf
	v_max_f32_e32 v40, v40, v41
	s_nop 0
	v_readlane_b32 s4, v40, 63
	s_nop 1
	v_max_f32_e32 v42, s4, v59
	v_sub_f32_e32 v176, v176, v42
	v_mul_f32_e32 v176, 0x3fb8aa3b, v176
	v_sub_f32_e32 v184, v184, v42
	v_mul_f32_e32 v184, 0x3fb8aa3b, v184
	v_sub_f32_e32 v192, v192, v42
	v_mul_f32_e32 v192, 0x3fb8aa3b, v192
	v_exp_f32_e32 v176, v176
	v_exp_f32_e32 v184, v184
	v_exp_f32_e32 v192, v192
	v_add_f32_e32 v43, v176, v184
	v_sub_f32_e32 v38, v59, v42
	v_add_f32_e32 v43, v43, v192
	v_mul_f32_e32 v38, 0x3fb8aa3b, v38
	v_exp_f32_e32 v38, v38
	s_nop 1
	v_add_f32_dpp v43, v43, v43 quad_perm:[1,0,3,2] row_mask:0xf bank_mask:0xf bound_ctrl:1
	s_nop 1
	v_add_f32_dpp v43, v43, v43 quad_perm:[2,3,0,1] row_mask:0xf bank_mask:0xf bound_ctrl:1
	s_nop 1
	v_add_f32_dpp v43, v43, v43 row_half_mirror row_mask:0xf bank_mask:0xf bound_ctrl:1
	s_nop 1
	v_add_f32_dpp v43, v43, v43 row_mirror row_mask:0xf bank_mask:0xf bound_ctrl:1
	v_mov_b32_e32 v41, 0
	s_nop 1
	v_mov_b32_dpp v41, v43 row_bcast:15 row_mask:0xa bank_mask:0xf
	v_add_f32_e32 v43, v43, v41
	v_mov_b32_e32 v41, 0
	s_nop 1
	v_mov_b32_dpp v41, v43 row_bcast:31 row_mask:0xc bank_mask:0xf
	v_add_f32_e32 v43, v43, v41
	s_nop 0
	v_readlane_b32 s5, v43, 63
	s_nop 1
	v_add_f32_e32 v200, s5, v38
	v_add_u32_e32 v38, 1, v10
	v_cvt_f32_i32_e32 v39, v38
	v_cmp_gt_u32_e32 vcc, s3, v38
	v_mul_f32_e32 v39, v14, v39
	v_fma_f32 v177, v177, s52, -v39
	v_cndmask_b32_e32 v177, v241, v177, vcc
	v_add_u32_e32 v38, 0xffffffc1, v10
	v_cvt_f32_i32_e32 v39, v38
	v_cmp_gt_u32_e32 vcc, s3, v38
	v_mul_f32_e32 v39, v14, v39
	v_fma_f32 v185, v185, s52, -v39
	v_cndmask_b32_e32 v185, v241, v185, vcc
	v_add_u32_e32 v38, 0xffffff81, v10
	v_cvt_f32_i32_e32 v39, v38
	v_cmp_gt_u32_e32 vcc, s3, v38
	v_mul_f32_e32 v39, v14, v39
	v_fma_f32 v193, v193, s52, -v39
	s_and_b64 vcc, s[40:41], vcc
	v_cndmask_b32_e32 v193, v241, v193, vcc
	v_max3_f32 v40, v177, v185, v193
	v_mov_b32_e32 v41, v241
	s_nop 1
	v_mov_b32_dpp v41, v40 quad_perm:[1,0,3,2] row_mask:0xf bank_mask:0xf
	v_max_f32_e32 v40, v40, v41
	v_mov_b32_e32 v41, v241
	s_nop 1
	v_mov_b32_dpp v41, v40 quad_perm:[2,3,0,1] row_mask:0xf bank_mask:0xf
	v_max_f32_e32 v40, v40, v41
	v_mov_b32_e32 v41, v241
	s_nop 1
	v_mov_b32_dpp v41, v40 row_half_mirror row_mask:0xf bank_mask:0xf
	v_max_f32_e32 v40, v40, v41
	v_mov_b32_e32 v41, v241
	s_nop 1
	v_mov_b32_dpp v41, v40 row_mirror row_mask:0xf bank_mask:0xf
	v_max_f32_e32 v40, v40, v41
	v_mov_b32_e32 v41, v241
	s_nop 1
	v_mov_b32_dpp v41, v40 row_bcast:15 row_mask:0xa bank_mask:0xf
	v_max_f32_e32 v40, v40, v41
	v_mov_b32_e32 v41, v241
	s_nop 1
	v_mov_b32_dpp v41, v40 row_bcast:31 row_mask:0xc bank_mask:0xf
	v_max_f32_e32 v40, v40, v41
	s_nop 0
	v_readlane_b32 s4, v40, 63
	s_nop 1
	v_max_f32_e32 v42, s4, v59
	v_sub_f32_e32 v177, v177, v42
	v_mul_f32_e32 v177, 0x3fb8aa3b, v177
	v_sub_f32_e32 v185, v185, v42
	v_mul_f32_e32 v185, 0x3fb8aa3b, v185
	v_sub_f32_e32 v193, v193, v42
	v_mul_f32_e32 v193, 0x3fb8aa3b, v193
	v_exp_f32_e32 v177, v177
	v_exp_f32_e32 v185, v185
	v_exp_f32_e32 v193, v193
	v_add_f32_e32 v43, v177, v185
	v_sub_f32_e32 v38, v59, v42
	v_add_f32_e32 v43, v43, v193
	v_mul_f32_e32 v38, 0x3fb8aa3b, v38
	v_exp_f32_e32 v38, v38
	s_nop 1
	v_add_f32_dpp v43, v43, v43 quad_perm:[1,0,3,2] row_mask:0xf bank_mask:0xf bound_ctrl:1
	s_nop 1
	v_add_f32_dpp v43, v43, v43 quad_perm:[2,3,0,1] row_mask:0xf bank_mask:0xf bound_ctrl:1
	s_nop 1
	v_add_f32_dpp v43, v43, v43 row_half_mirror row_mask:0xf bank_mask:0xf bound_ctrl:1
	s_nop 1
	v_add_f32_dpp v43, v43, v43 row_mirror row_mask:0xf bank_mask:0xf bound_ctrl:1
	v_mov_b32_e32 v41, 0
	s_nop 1
	v_mov_b32_dpp v41, v43 row_bcast:15 row_mask:0xa bank_mask:0xf
	v_add_f32_e32 v43, v43, v41
	v_mov_b32_e32 v41, 0
	s_nop 1
	v_mov_b32_dpp v41, v43 row_bcast:31 row_mask:0xc bank_mask:0xf
	v_add_f32_e32 v43, v43, v41
	s_nop 0
	v_readlane_b32 s5, v43, 63
	s_nop 1
	v_add_f32_e32 v201, s5, v38
	v_add_u32_e32 v38, 2, v10
	v_cvt_f32_i32_e32 v39, v38
	v_cmp_gt_u32_e32 vcc, s3, v38
	v_mul_f32_e32 v39, v14, v39
	v_fma_f32 v178, v178, s52, -v39
	v_cndmask_b32_e32 v178, v241, v178, vcc
	v_add_u32_e32 v38, 0xffffffc2, v10
	v_cvt_f32_i32_e32 v39, v38
	v_cmp_gt_u32_e32 vcc, s3, v38
	v_mul_f32_e32 v39, v14, v39
	v_fma_f32 v186, v186, s52, -v39
	v_cndmask_b32_e32 v186, v241, v186, vcc
	v_add_u32_e32 v38, 0xffffff82, v10
	v_cvt_f32_i32_e32 v39, v38
	v_cmp_gt_u32_e32 vcc, s3, v38
	v_mul_f32_e32 v39, v14, v39
	v_fma_f32 v194, v194, s52, -v39
	s_and_b64 vcc, s[40:41], vcc
	v_cndmask_b32_e32 v194, v241, v194, vcc
	v_max3_f32 v40, v178, v186, v194
	v_mov_b32_e32 v41, v241
	s_nop 1
	v_mov_b32_dpp v41, v40 quad_perm:[1,0,3,2] row_mask:0xf bank_mask:0xf
	v_max_f32_e32 v40, v40, v41
	v_mov_b32_e32 v41, v241
	s_nop 1
	v_mov_b32_dpp v41, v40 quad_perm:[2,3,0,1] row_mask:0xf bank_mask:0xf
	v_max_f32_e32 v40, v40, v41
	v_mov_b32_e32 v41, v241
	s_nop 1
	v_mov_b32_dpp v41, v40 row_half_mirror row_mask:0xf bank_mask:0xf
	v_max_f32_e32 v40, v40, v41
	v_mov_b32_e32 v41, v241
	s_nop 1
	v_mov_b32_dpp v41, v40 row_mirror row_mask:0xf bank_mask:0xf
	v_max_f32_e32 v40, v40, v41
	v_mov_b32_e32 v41, v241
	s_nop 1
	v_mov_b32_dpp v41, v40 row_bcast:15 row_mask:0xa bank_mask:0xf
	v_max_f32_e32 v40, v40, v41
	v_mov_b32_e32 v41, v241
	s_nop 1
	v_mov_b32_dpp v41, v40 row_bcast:31 row_mask:0xc bank_mask:0xf
	v_max_f32_e32 v40, v40, v41
	s_nop 0
	v_readlane_b32 s4, v40, 63
	s_nop 1
	v_max_f32_e32 v42, s4, v59
	v_sub_f32_e32 v178, v178, v42
	v_mul_f32_e32 v178, 0x3fb8aa3b, v178
	v_sub_f32_e32 v186, v186, v42
	v_mul_f32_e32 v186, 0x3fb8aa3b, v186
	v_sub_f32_e32 v194, v194, v42
	v_mul_f32_e32 v194, 0x3fb8aa3b, v194
	v_exp_f32_e32 v178, v178
	v_exp_f32_e32 v186, v186
	v_exp_f32_e32 v194, v194
	v_add_f32_e32 v43, v178, v186
	v_sub_f32_e32 v38, v59, v42
	v_add_f32_e32 v43, v43, v194
	v_mul_f32_e32 v38, 0x3fb8aa3b, v38
	v_exp_f32_e32 v38, v38
	s_nop 1
	v_add_f32_dpp v43, v43, v43 quad_perm:[1,0,3,2] row_mask:0xf bank_mask:0xf bound_ctrl:1
	s_nop 1
	v_add_f32_dpp v43, v43, v43 quad_perm:[2,3,0,1] row_mask:0xf bank_mask:0xf bound_ctrl:1
	s_nop 1
	v_add_f32_dpp v43, v43, v43 row_half_mirror row_mask:0xf bank_mask:0xf bound_ctrl:1
	s_nop 1
	v_add_f32_dpp v43, v43, v43 row_mirror row_mask:0xf bank_mask:0xf bound_ctrl:1
	v_mov_b32_e32 v41, 0
	s_nop 1
	v_mov_b32_dpp v41, v43 row_bcast:15 row_mask:0xa bank_mask:0xf
	v_add_f32_e32 v43, v43, v41
	v_mov_b32_e32 v41, 0
	s_nop 1
	v_mov_b32_dpp v41, v43 row_bcast:31 row_mask:0xc bank_mask:0xf
	v_add_f32_e32 v43, v43, v41
	s_nop 0
	v_readlane_b32 s5, v43, 63
	s_nop 1
	v_add_f32_e32 v202, s5, v38
	v_add_u32_e32 v38, 3, v10
	v_cvt_f32_i32_e32 v39, v38
	v_cmp_gt_u32_e32 vcc, s3, v38
	v_mul_f32_e32 v39, v14, v39
	v_fma_f32 v179, v179, s52, -v39
	v_cndmask_b32_e32 v179, v241, v179, vcc
	v_add_u32_e32 v38, 0xffffffc3, v10
	v_cvt_f32_i32_e32 v39, v38
	v_cmp_gt_u32_e32 vcc, s3, v38
	v_mul_f32_e32 v39, v14, v39
	v_fma_f32 v187, v187, s52, -v39
	v_cndmask_b32_e32 v187, v241, v187, vcc
	v_add_u32_e32 v38, 0xffffff83, v10
	v_cvt_f32_i32_e32 v39, v38
	v_cmp_gt_u32_e32 vcc, s3, v38
	v_mul_f32_e32 v39, v14, v39
	v_fma_f32 v195, v195, s52, -v39
	s_and_b64 vcc, s[40:41], vcc
	v_cndmask_b32_e32 v195, v241, v195, vcc
	v_max3_f32 v40, v179, v187, v195
	v_mov_b32_e32 v41, v241
	s_nop 1
	v_mov_b32_dpp v41, v40 quad_perm:[1,0,3,2] row_mask:0xf bank_mask:0xf
	v_max_f32_e32 v40, v40, v41
	v_mov_b32_e32 v41, v241
	s_nop 1
	v_mov_b32_dpp v41, v40 quad_perm:[2,3,0,1] row_mask:0xf bank_mask:0xf
	v_max_f32_e32 v40, v40, v41
	v_mov_b32_e32 v41, v241
	s_nop 1
	v_mov_b32_dpp v41, v40 row_half_mirror row_mask:0xf bank_mask:0xf
	v_max_f32_e32 v40, v40, v41
	v_mov_b32_e32 v41, v241
	s_nop 1
	v_mov_b32_dpp v41, v40 row_mirror row_mask:0xf bank_mask:0xf
	v_max_f32_e32 v40, v40, v41
	v_mov_b32_e32 v41, v241
	s_nop 1
	v_mov_b32_dpp v41, v40 row_bcast:15 row_mask:0xa bank_mask:0xf
	v_max_f32_e32 v40, v40, v41
	v_mov_b32_e32 v41, v241
	s_nop 1
	v_mov_b32_dpp v41, v40 row_bcast:31 row_mask:0xc bank_mask:0xf
	v_max_f32_e32 v40, v40, v41
	s_nop 0
	v_readlane_b32 s4, v40, 63
	s_nop 1
	v_max_f32_e32 v42, s4, v59
	v_sub_f32_e32 v179, v179, v42
	v_mul_f32_e32 v179, 0x3fb8aa3b, v179
	v_sub_f32_e32 v187, v187, v42
	v_mul_f32_e32 v187, 0x3fb8aa3b, v187
	v_sub_f32_e32 v195, v195, v42
	v_mul_f32_e32 v195, 0x3fb8aa3b, v195
	v_exp_f32_e32 v179, v179
	v_exp_f32_e32 v187, v187
	v_exp_f32_e32 v195, v195
	v_add_f32_e32 v43, v179, v187
	v_sub_f32_e32 v38, v59, v42
	v_add_f32_e32 v43, v43, v195
	v_mul_f32_e32 v38, 0x3fb8aa3b, v38
	v_exp_f32_e32 v38, v38
	s_nop 1
	v_add_f32_dpp v43, v43, v43 quad_perm:[1,0,3,2] row_mask:0xf bank_mask:0xf bound_ctrl:1
	s_nop 1
	v_add_f32_dpp v43, v43, v43 quad_perm:[2,3,0,1] row_mask:0xf bank_mask:0xf bound_ctrl:1
	s_nop 1
	v_add_f32_dpp v43, v43, v43 row_half_mirror row_mask:0xf bank_mask:0xf bound_ctrl:1
	s_nop 1
	v_add_f32_dpp v43, v43, v43 row_mirror row_mask:0xf bank_mask:0xf bound_ctrl:1
	v_mov_b32_e32 v41, 0
	s_nop 1
	v_mov_b32_dpp v41, v43 row_bcast:15 row_mask:0xa bank_mask:0xf
	v_add_f32_e32 v43, v43, v41
	v_mov_b32_e32 v41, 0
	s_nop 1
	v_mov_b32_dpp v41, v43 row_bcast:31 row_mask:0xc bank_mask:0xf
	v_add_f32_e32 v43, v43, v41
	s_nop 0
	v_readlane_b32 s5, v43, 63
	s_nop 1
	v_add_f32_e32 v203, s5, v38
	v_add_u32_e32 v38, 4, v10
	v_cvt_f32_i32_e32 v39, v38
	v_cmp_gt_u32_e32 vcc, s3, v38
	v_mul_f32_e32 v39, v14, v39
	v_fma_f32 v180, v180, s52, -v39
	v_cndmask_b32_e32 v180, v241, v180, vcc
	v_add_u32_e32 v38, 0xffffffc4, v10
	v_cvt_f32_i32_e32 v39, v38
	v_cmp_gt_u32_e32 vcc, s3, v38
	v_mul_f32_e32 v39, v14, v39
	v_fma_f32 v188, v188, s52, -v39
	v_cndmask_b32_e32 v188, v241, v188, vcc
	v_add_u32_e32 v38, 0xffffff84, v10
	v_cvt_f32_i32_e32 v39, v38
	v_cmp_gt_u32_e32 vcc, s3, v38
	v_mul_f32_e32 v39, v14, v39
	v_fma_f32 v196, v196, s52, -v39
	s_and_b64 vcc, s[40:41], vcc
	v_cndmask_b32_e32 v196, v241, v196, vcc
	v_max3_f32 v40, v180, v188, v196
	v_mov_b32_e32 v41, v241
	s_nop 1
	v_mov_b32_dpp v41, v40 quad_perm:[1,0,3,2] row_mask:0xf bank_mask:0xf
	v_max_f32_e32 v40, v40, v41
	v_mov_b32_e32 v41, v241
	s_nop 1
	v_mov_b32_dpp v41, v40 quad_perm:[2,3,0,1] row_mask:0xf bank_mask:0xf
	v_max_f32_e32 v40, v40, v41
	v_mov_b32_e32 v41, v241
	s_nop 1
	v_mov_b32_dpp v41, v40 row_half_mirror row_mask:0xf bank_mask:0xf
	v_max_f32_e32 v40, v40, v41
	v_mov_b32_e32 v41, v241
	s_nop 1
	v_mov_b32_dpp v41, v40 row_mirror row_mask:0xf bank_mask:0xf
	v_max_f32_e32 v40, v40, v41
	v_mov_b32_e32 v41, v241
	s_nop 1
	v_mov_b32_dpp v41, v40 row_bcast:15 row_mask:0xa bank_mask:0xf
	v_max_f32_e32 v40, v40, v41
	v_mov_b32_e32 v41, v241
	s_nop 1
	v_mov_b32_dpp v41, v40 row_bcast:31 row_mask:0xc bank_mask:0xf
	v_max_f32_e32 v40, v40, v41
	s_nop 0
	v_readlane_b32 s4, v40, 63
	s_nop 1
	v_max_f32_e32 v42, s4, v59
	v_sub_f32_e32 v180, v180, v42
	v_mul_f32_e32 v180, 0x3fb8aa3b, v180
	v_sub_f32_e32 v188, v188, v42
	v_mul_f32_e32 v188, 0x3fb8aa3b, v188
	v_sub_f32_e32 v196, v196, v42
	v_mul_f32_e32 v196, 0x3fb8aa3b, v196
	v_exp_f32_e32 v180, v180
	v_exp_f32_e32 v188, v188
	v_exp_f32_e32 v196, v196
	v_add_f32_e32 v43, v180, v188
	v_sub_f32_e32 v38, v59, v42
	v_add_f32_e32 v43, v43, v196
	v_mul_f32_e32 v38, 0x3fb8aa3b, v38
	v_exp_f32_e32 v38, v38
	s_nop 1
	v_add_f32_dpp v43, v43, v43 quad_perm:[1,0,3,2] row_mask:0xf bank_mask:0xf bound_ctrl:1
	s_nop 1
	v_add_f32_dpp v43, v43, v43 quad_perm:[2,3,0,1] row_mask:0xf bank_mask:0xf bound_ctrl:1
	s_nop 1
	v_add_f32_dpp v43, v43, v43 row_half_mirror row_mask:0xf bank_mask:0xf bound_ctrl:1
	s_nop 1
	v_add_f32_dpp v43, v43, v43 row_mirror row_mask:0xf bank_mask:0xf bound_ctrl:1
	v_mov_b32_e32 v41, 0
	s_nop 1
	v_mov_b32_dpp v41, v43 row_bcast:15 row_mask:0xa bank_mask:0xf
	v_add_f32_e32 v43, v43, v41
	v_mov_b32_e32 v41, 0
	s_nop 1
	v_mov_b32_dpp v41, v43 row_bcast:31 row_mask:0xc bank_mask:0xf
	v_add_f32_e32 v43, v43, v41
	s_nop 0
	v_readlane_b32 s5, v43, 63
	s_nop 1
	v_add_f32_e32 v204, s5, v38
	v_add_u32_e32 v38, 5, v10
	v_cvt_f32_i32_e32 v39, v38
	v_cmp_gt_u32_e32 vcc, s3, v38
	v_mul_f32_e32 v39, v14, v39
	v_fma_f32 v181, v181, s52, -v39
	v_cndmask_b32_e32 v181, v241, v181, vcc
	v_add_u32_e32 v38, 0xffffffc5, v10
	v_cvt_f32_i32_e32 v39, v38
	v_cmp_gt_u32_e32 vcc, s3, v38
	v_mul_f32_e32 v39, v14, v39
	v_fma_f32 v189, v189, s52, -v39
	v_cndmask_b32_e32 v189, v241, v189, vcc
	v_add_u32_e32 v38, 0xffffff85, v10
	v_cvt_f32_i32_e32 v39, v38
	v_cmp_gt_u32_e32 vcc, s3, v38
	v_mul_f32_e32 v39, v14, v39
	v_fma_f32 v197, v197, s52, -v39
	s_and_b64 vcc, s[40:41], vcc
	v_cndmask_b32_e32 v197, v241, v197, vcc
	v_max3_f32 v40, v181, v189, v197
	v_mov_b32_e32 v41, v241
	s_nop 1
	v_mov_b32_dpp v41, v40 quad_perm:[1,0,3,2] row_mask:0xf bank_mask:0xf
	v_max_f32_e32 v40, v40, v41
	v_mov_b32_e32 v41, v241
	s_nop 1
	v_mov_b32_dpp v41, v40 quad_perm:[2,3,0,1] row_mask:0xf bank_mask:0xf
	v_max_f32_e32 v40, v40, v41
	v_mov_b32_e32 v41, v241
	s_nop 1
	v_mov_b32_dpp v41, v40 row_half_mirror row_mask:0xf bank_mask:0xf
	v_max_f32_e32 v40, v40, v41
	v_mov_b32_e32 v41, v241
	s_nop 1
	v_mov_b32_dpp v41, v40 row_mirror row_mask:0xf bank_mask:0xf
	v_max_f32_e32 v40, v40, v41
	v_mov_b32_e32 v41, v241
	s_nop 1
	v_mov_b32_dpp v41, v40 row_bcast:15 row_mask:0xa bank_mask:0xf
	v_max_f32_e32 v40, v40, v41
	v_mov_b32_e32 v41, v241
	s_nop 1
	v_mov_b32_dpp v41, v40 row_bcast:31 row_mask:0xc bank_mask:0xf
	v_max_f32_e32 v40, v40, v41
	s_nop 0
	v_readlane_b32 s4, v40, 63
	s_nop 1
	v_max_f32_e32 v42, s4, v59
	v_sub_f32_e32 v181, v181, v42
	v_mul_f32_e32 v181, 0x3fb8aa3b, v181
	v_sub_f32_e32 v189, v189, v42
	v_mul_f32_e32 v189, 0x3fb8aa3b, v189
	v_sub_f32_e32 v197, v197, v42
	v_mul_f32_e32 v197, 0x3fb8aa3b, v197
	v_exp_f32_e32 v181, v181
	v_exp_f32_e32 v189, v189
	v_exp_f32_e32 v197, v197
	v_add_f32_e32 v43, v181, v189
	v_sub_f32_e32 v38, v59, v42
	v_add_f32_e32 v43, v43, v197
	v_mul_f32_e32 v38, 0x3fb8aa3b, v38
	v_exp_f32_e32 v38, v38
	s_nop 1
	v_add_f32_dpp v43, v43, v43 quad_perm:[1,0,3,2] row_mask:0xf bank_mask:0xf bound_ctrl:1
	s_nop 1
	v_add_f32_dpp v43, v43, v43 quad_perm:[2,3,0,1] row_mask:0xf bank_mask:0xf bound_ctrl:1
	s_nop 1
	v_add_f32_dpp v43, v43, v43 row_half_mirror row_mask:0xf bank_mask:0xf bound_ctrl:1
	s_nop 1
	v_add_f32_dpp v43, v43, v43 row_mirror row_mask:0xf bank_mask:0xf bound_ctrl:1
	v_mov_b32_e32 v41, 0
	s_nop 1
	v_mov_b32_dpp v41, v43 row_bcast:15 row_mask:0xa bank_mask:0xf
	v_add_f32_e32 v43, v43, v41
	v_mov_b32_e32 v41, 0
	s_nop 1
	v_mov_b32_dpp v41, v43 row_bcast:31 row_mask:0xc bank_mask:0xf
	v_add_f32_e32 v43, v43, v41
	s_nop 0
	v_readlane_b32 s5, v43, 63
	s_nop 1
	v_add_f32_e32 v205, s5, v38
	v_add_u32_e32 v38, 6, v10
	v_cvt_f32_i32_e32 v39, v38
	v_cmp_gt_u32_e32 vcc, s3, v38
	v_mul_f32_e32 v39, v14, v39
	v_fma_f32 v182, v182, s52, -v39
	v_cndmask_b32_e32 v182, v241, v182, vcc
	v_add_u32_e32 v38, 0xffffffc6, v10
	v_cvt_f32_i32_e32 v39, v38
	v_cmp_gt_u32_e32 vcc, s3, v38
	v_mul_f32_e32 v39, v14, v39
	v_fma_f32 v190, v190, s52, -v39
	v_cndmask_b32_e32 v190, v241, v190, vcc
	v_add_u32_e32 v38, 0xffffff86, v10
	v_cvt_f32_i32_e32 v39, v38
	v_cmp_gt_u32_e32 vcc, s3, v38
	v_mul_f32_e32 v39, v14, v39
	v_fma_f32 v198, v198, s52, -v39
	s_and_b64 vcc, s[40:41], vcc
	v_cndmask_b32_e32 v198, v241, v198, vcc
	v_max3_f32 v40, v182, v190, v198
	v_mov_b32_e32 v41, v241
	s_nop 1
	v_mov_b32_dpp v41, v40 quad_perm:[1,0,3,2] row_mask:0xf bank_mask:0xf
	v_max_f32_e32 v40, v40, v41
	v_mov_b32_e32 v41, v241
	s_nop 1
	v_mov_b32_dpp v41, v40 quad_perm:[2,3,0,1] row_mask:0xf bank_mask:0xf
	v_max_f32_e32 v40, v40, v41
	v_mov_b32_e32 v41, v241
	s_nop 1
	v_mov_b32_dpp v41, v40 row_half_mirror row_mask:0xf bank_mask:0xf
	v_max_f32_e32 v40, v40, v41
	v_mov_b32_e32 v41, v241
	s_nop 1
	v_mov_b32_dpp v41, v40 row_mirror row_mask:0xf bank_mask:0xf
	v_max_f32_e32 v40, v40, v41
	v_mov_b32_e32 v41, v241
	s_nop 1
	v_mov_b32_dpp v41, v40 row_bcast:15 row_mask:0xa bank_mask:0xf
	v_max_f32_e32 v40, v40, v41
	v_mov_b32_e32 v41, v241
	s_nop 1
	v_mov_b32_dpp v41, v40 row_bcast:31 row_mask:0xc bank_mask:0xf
	v_max_f32_e32 v40, v40, v41
	s_nop 0
	v_readlane_b32 s4, v40, 63
	s_nop 1
	v_max_f32_e32 v42, s4, v59
	v_sub_f32_e32 v182, v182, v42
	v_mul_f32_e32 v182, 0x3fb8aa3b, v182
	v_sub_f32_e32 v190, v190, v42
	v_mul_f32_e32 v190, 0x3fb8aa3b, v190
	v_sub_f32_e32 v198, v198, v42
	v_mul_f32_e32 v198, 0x3fb8aa3b, v198
	v_exp_f32_e32 v182, v182
	v_exp_f32_e32 v190, v190
	v_exp_f32_e32 v198, v198
	v_add_f32_e32 v43, v182, v190
	v_sub_f32_e32 v38, v59, v42
	v_add_f32_e32 v43, v43, v198
	v_mul_f32_e32 v38, 0x3fb8aa3b, v38
	v_exp_f32_e32 v38, v38
	s_nop 1
	v_add_f32_dpp v43, v43, v43 quad_perm:[1,0,3,2] row_mask:0xf bank_mask:0xf bound_ctrl:1
	s_nop 1
	v_add_f32_dpp v43, v43, v43 quad_perm:[2,3,0,1] row_mask:0xf bank_mask:0xf bound_ctrl:1
	s_nop 1
	v_add_f32_dpp v43, v43, v43 row_half_mirror row_mask:0xf bank_mask:0xf bound_ctrl:1
	s_nop 1
	v_add_f32_dpp v43, v43, v43 row_mirror row_mask:0xf bank_mask:0xf bound_ctrl:1
	v_mov_b32_e32 v41, 0
	s_nop 1
	v_mov_b32_dpp v41, v43 row_bcast:15 row_mask:0xa bank_mask:0xf
	v_add_f32_e32 v43, v43, v41
	v_mov_b32_e32 v41, 0
	s_nop 1
	v_mov_b32_dpp v41, v43 row_bcast:31 row_mask:0xc bank_mask:0xf
	v_add_f32_e32 v43, v43, v41
	s_nop 0
	v_readlane_b32 s5, v43, 63
	s_nop 1
	v_add_f32_e32 v206, s5, v38
	v_add_u32_e32 v38, 7, v10
	v_cvt_f32_i32_e32 v39, v38
	v_cmp_gt_u32_e32 vcc, s3, v38
	v_mul_f32_e32 v39, v14, v39
	v_fma_f32 v183, v183, s52, -v39
	v_cndmask_b32_e32 v183, v241, v183, vcc
	v_add_u32_e32 v38, 0xffffffc7, v10
	v_cvt_f32_i32_e32 v39, v38
	v_cmp_gt_u32_e32 vcc, s3, v38
	v_mul_f32_e32 v39, v14, v39
	v_fma_f32 v191, v191, s52, -v39
	v_cndmask_b32_e32 v191, v241, v191, vcc
	v_add_u32_e32 v38, 0xffffff87, v10
	v_cvt_f32_i32_e32 v39, v38
	v_cmp_gt_u32_e32 vcc, s3, v38
	v_mul_f32_e32 v39, v14, v39
	v_fma_f32 v199, v199, s52, -v39
	s_and_b64 vcc, s[40:41], vcc
	v_cndmask_b32_e32 v199, v241, v199, vcc
	v_max3_f32 v40, v183, v191, v199
	v_mov_b32_e32 v41, v241
	s_nop 1
	v_mov_b32_dpp v41, v40 quad_perm:[1,0,3,2] row_mask:0xf bank_mask:0xf
	v_max_f32_e32 v40, v40, v41
	v_mov_b32_e32 v41, v241
	s_nop 1
	v_mov_b32_dpp v41, v40 quad_perm:[2,3,0,1] row_mask:0xf bank_mask:0xf
	v_max_f32_e32 v40, v40, v41
	v_mov_b32_e32 v41, v241
	s_nop 1
	v_mov_b32_dpp v41, v40 row_half_mirror row_mask:0xf bank_mask:0xf
	v_max_f32_e32 v40, v40, v41
	v_mov_b32_e32 v41, v241
	s_nop 1
	v_mov_b32_dpp v41, v40 row_mirror row_mask:0xf bank_mask:0xf
	v_max_f32_e32 v40, v40, v41
	v_mov_b32_e32 v41, v241
	s_nop 1
	v_mov_b32_dpp v41, v40 row_bcast:15 row_mask:0xa bank_mask:0xf
	v_max_f32_e32 v40, v40, v41
	v_mov_b32_e32 v41, v241
	s_nop 1
	v_mov_b32_dpp v41, v40 row_bcast:31 row_mask:0xc bank_mask:0xf
	v_max_f32_e32 v40, v40, v41
	s_nop 0
	v_readlane_b32 s4, v40, 63
	s_nop 1
	v_max_f32_e32 v42, s4, v59
	v_sub_f32_e32 v183, v183, v42
	v_mul_f32_e32 v183, 0x3fb8aa3b, v183
	v_sub_f32_e32 v191, v191, v42
	v_mul_f32_e32 v191, 0x3fb8aa3b, v191
	v_sub_f32_e32 v199, v199, v42
	v_mul_f32_e32 v199, 0x3fb8aa3b, v199
	v_exp_f32_e32 v183, v183
	v_exp_f32_e32 v191, v191
	v_exp_f32_e32 v199, v199
	v_add_f32_e32 v43, v183, v191
	v_sub_f32_e32 v38, v59, v42
	v_add_f32_e32 v43, v43, v199
	v_mul_f32_e32 v38, 0x3fb8aa3b, v38
	v_exp_f32_e32 v38, v38
	s_nop 1
	v_add_f32_dpp v43, v43, v43 quad_perm:[1,0,3,2] row_mask:0xf bank_mask:0xf bound_ctrl:1
	s_nop 1
	v_add_f32_dpp v43, v43, v43 quad_perm:[2,3,0,1] row_mask:0xf bank_mask:0xf bound_ctrl:1
	s_nop 1
	v_add_f32_dpp v43, v43, v43 row_half_mirror row_mask:0xf bank_mask:0xf bound_ctrl:1
	s_nop 1
	v_add_f32_dpp v43, v43, v43 row_mirror row_mask:0xf bank_mask:0xf bound_ctrl:1
	v_mov_b32_e32 v41, 0
	s_nop 1
	v_mov_b32_dpp v41, v43 row_bcast:15 row_mask:0xa bank_mask:0xf
	v_add_f32_e32 v43, v43, v41
	v_mov_b32_e32 v41, 0
	s_nop 1
	v_mov_b32_dpp v41, v43 row_bcast:31 row_mask:0xc bank_mask:0xf
	v_add_f32_e32 v43, v43, v41
	s_nop 0
	v_readlane_b32 s5, v43, 63
	s_nop 1
	v_add_f32_e32 v207, s5, v38
	s_lshl_b32 s30, s95, 2
	s_add_i32 s30, s30, 0xfffd0000
	v_lshl_add_u32 v38, v108, 5, s30
	ds_write_b128 v38, v[176:179]
	ds_write_b128 v38, v[180:183] offset:16
	ds_write_b128 v38, v[184:187] offset:2048
	ds_write_b128 v38, v[188:191] offset:2064
	s_mov_b64 s[44:45], exec
	s_mov_b64 exec, s[40:41]
	v_lshl_add_u32 v39, v108, 5, s95
	ds_write_b128 v39, v[192:195]
	ds_write_b128 v39, v[196:199] offset:16
	s_mov_b64 exec, s[44:45]
	v_lshrrev_b32_e32 v40, 4, v108
	v_and_b32_e32 v41, 7, v108
	v_lshlrev_b32_e32 v42, 5, v40
	v_lshl_add_u32 v42, v41, 2, v42
	v_add_u32_e32 v43, s30, v42
	v_add_u32_e32 v42, s95, v42
	v_and_b32_e32 v41, 15, v108
	v_lshlrev_b32_e32 v35, 8, v40
	v_lshl_add_u32 v35, v41, 2, v35
	v_add_u32_e32 v35, 0x9080, v35
	v_mov_b32_e32 v208, 0
	v_mov_b32_e32 v209, 0
	v_mov_b32_e32 v210, 0
	v_mov_b32_e32 v211, 0
	v_mov_b32_e32 v212, 0
	v_mov_b32_e32 v213, 0
	v_mov_b32_e32 v214, 0
	v_mov_b32_e32 v215, 0
	v_mov_b32_e32 v216, 0
	v_mov_b32_e32 v217, 0
	v_mov_b32_e32 v218, 0
	v_mov_b32_e32 v219, 0
	v_mov_b32_e32 v220, 0
	v_mov_b32_e32 v221, 0
	v_mov_b32_e32 v222, 0
	v_mov_b32_e32 v223, 0
	s_waitcnt lgkmcnt(0)
	ds_read_b32 v60, v43 offset:0
	ds_read_b32 v61, v35 offset:0
	ds_read_b32 v62, v35 offset:64
	ds_read_b32 v63, v35 offset:128
	ds_read_b32 v64, v35 offset:192
	ds_read_b32 v65, v43 offset:128
	ds_read_b32 v66, v35 offset:1024
	ds_read_b32 v67, v35 offset:1088
	ds_read_b32 v68, v35 offset:1152
	ds_read_b32 v69, v35 offset:1216
	ds_read_b32 v70, v43 offset:256
	ds_read_b32 v71, v35 offset:2048
	ds_read_b32 v72, v35 offset:2112
	ds_read_b32 v73, v35 offset:2176
	ds_read_b32 v74, v35 offset:2240
	s_waitcnt lgkmcnt(10)
	v_mfma_f32_16x16x4_f32 v[208:211], v60, v61, v[208:211]
	v_mfma_f32_16x16x4_f32 v[212:215], v60, v62, v[212:215]
	v_mfma_f32_16x16x4_f32 v[216:219], v60, v63, v[216:219]
	v_mfma_f32_16x16x4_f32 v[220:223], v60, v64, v[220:223]
	ds_read_b32 v60, v43 offset:384
	ds_read_b32 v61, v35 offset:3072
	ds_read_b32 v62, v35 offset:3136
	ds_read_b32 v63, v35 offset:3200
	ds_read_b32 v64, v35 offset:3264
	s_waitcnt lgkmcnt(10)
	v_mfma_f32_16x16x4_f32 v[208:211], v65, v66, v[208:211]
	v_mfma_f32_16x16x4_f32 v[212:215], v65, v67, v[212:215]
	v_mfma_f32_16x16x4_f32 v[216:219], v65, v68, v[216:219]
	v_mfma_f32_16x16x4_f32 v[220:223], v65, v69, v[220:223]
	ds_read_b32 v65, v43 offset:512
	ds_read_b32 v66, v35 offset:4096
	ds_read_b32 v67, v35 offset:4160
	ds_read_b32 v68, v35 offset:4224
	ds_read_b32 v69, v35 offset:4288
	s_waitcnt lgkmcnt(10)
	v_mfma_f32_16x16x4_f32 v[208:211], v70, v71, v[208:211]
	v_mfma_f32_16x16x4_f32 v[212:215], v70, v72, v[212:215]
	v_mfma_f32_16x16x4_f32 v[216:219], v70, v73, v[216:219]
	v_mfma_f32_16x16x4_f32 v[220:223], v70, v74, v[220:223]
	ds_read_b32 v70, v43 offset:640
	ds_read_b32 v71, v35 offset:5120
	ds_read_b32 v72, v35 offset:5184
	ds_read_b32 v73, v35 offset:5248
	ds_read_b32 v74, v35 offset:5312
	s_waitcnt lgkmcnt(10)
	v_mfma_f32_16x16x4_f32 v[208:211], v60, v61, v[208:211]
	v_mfma_f32_16x16x4_f32 v[212:215], v60, v62, v[212:215]
	v_mfma_f32_16x16x4_f32 v[216:219], v60, v63, v[216:219]
	v_mfma_f32_16x16x4_f32 v[220:223], v60, v64, v[220:223]
	ds_read_b32 v60, v43 offset:768
	ds_read_b32 v61, v35 offset:6144
	ds_read_b32 v62, v35 offset:6208
	ds_read_b32 v63, v35 offset:6272
	ds_read_b32 v64, v35 offset:6336
	s_waitcnt lgkmcnt(10)
	v_mfma_f32_16x16x4_f32 v[208:211], v65, v66, v[208:211]
	v_mfma_f32_16x16x4_f32 v[212:215], v65, v67, v[212:215]
	v_mfma_f32_16x16x4_f32 v[216:219], v65, v68, v[216:219]
	v_mfma_f32_16x16x4_f32 v[220:223], v65, v69, v[220:223]
	ds_read_b32 v65, v43 offset:896
	ds_read_b32 v66, v35 offset:7168
	ds_read_b32 v67, v35 offset:7232
	ds_read_b32 v68, v35 offset:7296
	ds_read_b32 v69, v35 offset:7360
	s_waitcnt lgkmcnt(10)
	v_mfma_f32_16x16x4_f32 v[208:211], v70, v71, v[208:211]
	v_mfma_f32_16x16x4_f32 v[212:215], v70, v72, v[212:215]
	v_mfma_f32_16x16x4_f32 v[216:219], v70, v73, v[216:219]
	v_mfma_f32_16x16x4_f32 v[220:223], v70, v74, v[220:223]
	ds_read_b32 v70, v43 offset:1024
	ds_read_b32 v71, v35 offset:8192
	ds_read_b32 v72, v35 offset:8256
	ds_read_b32 v73, v35 offset:8320
	ds_read_b32 v74, v35 offset:8384
	s_waitcnt lgkmcnt(10)
	v_mfma_f32_16x16x4_f32 v[208:211], v60, v61, v[208:211]
	v_mfma_f32_16x16x4_f32 v[212:215], v60, v62, v[212:215]
	v_mfma_f32_16x16x4_f32 v[216:219], v60, v63, v[216:219]
	v_mfma_f32_16x16x4_f32 v[220:223], v60, v64, v[220:223]
	ds_read_b32 v60, v43 offset:1152
	ds_read_b32 v61, v35 offset:9216
	ds_read_b32 v62, v35 offset:9280
	ds_read_b32 v63, v35 offset:9344
	ds_read_b32 v64, v35 offset:9408
	s_waitcnt lgkmcnt(10)
	v_mfma_f32_16x16x4_f32 v[208:211], v65, v66, v[208:211]
	v_mfma_f32_16x16x4_f32 v[212:215], v65, v67, v[212:215]
	v_mfma_f32_16x16x4_f32 v[216:219], v65, v68, v[216:219]
	v_mfma_f32_16x16x4_f32 v[220:223], v65, v69, v[220:223]
	ds_read_b32 v65, v43 offset:1280
	ds_read_b32 v66, v35 offset:10240
	ds_read_b32 v67, v35 offset:10304
	ds_read_b32 v68, v35 offset:10368
	ds_read_b32 v69, v35 offset:10432
	s_waitcnt lgkmcnt(10)
	v_mfma_f32_16x16x4_f32 v[208:211], v70, v71, v[208:211]
	v_mfma_f32_16x16x4_f32 v[212:215], v70, v72, v[212:215]
	v_mfma_f32_16x16x4_f32 v[216:219], v70, v73, v[216:219]
	v_mfma_f32_16x16x4_f32 v[220:223], v70, v74, v[220:223]
	ds_read_b32 v70, v43 offset:1408
	ds_read_b32 v71, v35 offset:11264
	ds_read_b32 v72, v35 offset:11328
	ds_read_b32 v73, v35 offset:11392
	ds_read_b32 v74, v35 offset:11456
	s_waitcnt lgkmcnt(10)
	v_mfma_f32_16x16x4_f32 v[208:211], v60, v61, v[208:211]
	v_mfma_f32_16x16x4_f32 v[212:215], v60, v62, v[212:215]
	v_mfma_f32_16x16x4_f32 v[216:219], v60, v63, v[216:219]
	v_mfma_f32_16x16x4_f32 v[220:223], v60, v64, v[220:223]
	ds_read_b32 v60, v43 offset:1536
	ds_read_b32 v61, v35 offset:12288
	ds_read_b32 v62, v35 offset:12352
	ds_read_b32 v63, v35 offset:12416
	ds_read_b32 v64, v35 offset:12480
	s_waitcnt lgkmcnt(10)
	v_mfma_f32_16x16x4_f32 v[208:211], v65, v66, v[208:211]
	v_mfma_f32_16x16x4_f32 v[212:215], v65, v67, v[212:215]
	v_mfma_f32_16x16x4_f32 v[216:219], v65, v68, v[216:219]
	v_mfma_f32_16x16x4_f32 v[220:223], v65, v69, v[220:223]
	ds_read_b32 v65, v43 offset:1664
	ds_read_b32 v66, v35 offset:13312
	ds_read_b32 v67, v35 offset:13376
	ds_read_b32 v68, v35 offset:13440
	ds_read_b32 v69, v35 offset:13504
	s_waitcnt lgkmcnt(10)
	v_mfma_f32_16x16x4_f32 v[208:211], v70, v71, v[208:211]
	v_mfma_f32_16x16x4_f32 v[212:215], v70, v72, v[212:215]
	v_mfma_f32_16x16x4_f32 v[216:219], v70, v73, v[216:219]
	v_mfma_f32_16x16x4_f32 v[220:223], v70, v74, v[220:223]
	ds_read_b32 v70, v43 offset:1792
	ds_read_b32 v71, v35 offset:14336
	ds_read_b32 v72, v35 offset:14400
	ds_read_b32 v73, v35 offset:14464
	ds_read_b32 v74, v35 offset:14528
	s_waitcnt lgkmcnt(10)
	v_mfma_f32_16x16x4_f32 v[208:211], v60, v61, v[208:211]
	v_mfma_f32_16x16x4_f32 v[212:215], v60, v62, v[212:215]
	v_mfma_f32_16x16x4_f32 v[216:219], v60, v63, v[216:219]
	v_mfma_f32_16x16x4_f32 v[220:223], v60, v64, v[220:223]
	ds_read_b32 v60, v43 offset:1920
	ds_read_b32 v61, v35 offset:15360
	ds_read_b32 v62, v35 offset:15424
	ds_read_b32 v63, v35 offset:15488
	ds_read_b32 v64, v35 offset:15552
	s_waitcnt lgkmcnt(10)
	v_mfma_f32_16x16x4_f32 v[208:211], v65, v66, v[208:211]
	v_mfma_f32_16x16x4_f32 v[212:215], v65, v67, v[212:215]
	v_mfma_f32_16x16x4_f32 v[216:219], v65, v68, v[216:219]
	v_mfma_f32_16x16x4_f32 v[220:223], v65, v69, v[220:223]
	ds_read_b32 v65, v43 offset:2048
	ds_read_b32 v66, v35 offset:16384
	ds_read_b32 v67, v35 offset:16448
	ds_read_b32 v68, v35 offset:16512
	ds_read_b32 v69, v35 offset:16576
	s_waitcnt lgkmcnt(10)
	v_mfma_f32_16x16x4_f32 v[208:211], v70, v71, v[208:211]
	v_mfma_f32_16x16x4_f32 v[212:215], v70, v72, v[212:215]
	v_mfma_f32_16x16x4_f32 v[216:219], v70, v73, v[216:219]
	v_mfma_f32_16x16x4_f32 v[220:223], v70, v74, v[220:223]
	ds_read_b32 v70, v43 offset:2176
	ds_read_b32 v71, v35 offset:17408
	ds_read_b32 v72, v35 offset:17472
	ds_read_b32 v73, v35 offset:17536
	ds_read_b32 v74, v35 offset:17600
	s_waitcnt lgkmcnt(10)
	v_mfma_f32_16x16x4_f32 v[208:211], v60, v61, v[208:211]
	v_mfma_f32_16x16x4_f32 v[212:215], v60, v62, v[212:215]
	v_mfma_f32_16x16x4_f32 v[216:219], v60, v63, v[216:219]
	v_mfma_f32_16x16x4_f32 v[220:223], v60, v64, v[220:223]
	ds_read_b32 v60, v43 offset:2304
	ds_read_b32 v61, v35 offset:18432
	ds_read_b32 v62, v35 offset:18496
	ds_read_b32 v63, v35 offset:18560
	ds_read_b32 v64, v35 offset:18624
	s_waitcnt lgkmcnt(10)
	v_mfma_f32_16x16x4_f32 v[208:211], v65, v66, v[208:211]
	v_mfma_f32_16x16x4_f32 v[212:215], v65, v67, v[212:215]
	v_mfma_f32_16x16x4_f32 v[216:219], v65, v68, v[216:219]
	v_mfma_f32_16x16x4_f32 v[220:223], v65, v69, v[220:223]
	ds_read_b32 v65, v43 offset:2432
	ds_read_b32 v66, v35 offset:19456
	ds_read_b32 v67, v35 offset:19520
	ds_read_b32 v68, v35 offset:19584
	ds_read_b32 v69, v35 offset:19648
	s_waitcnt lgkmcnt(10)
	v_mfma_f32_16x16x4_f32 v[208:211], v70, v71, v[208:211]
	v_mfma_f32_16x16x4_f32 v[212:215], v70, v72, v[212:215]
	v_mfma_f32_16x16x4_f32 v[216:219], v70, v73, v[216:219]
	v_mfma_f32_16x16x4_f32 v[220:223], v70, v74, v[220:223]
	ds_read_b32 v70, v43 offset:2560
	ds_read_b32 v71, v35 offset:20480
	ds_read_b32 v72, v35 offset:20544
	ds_read_b32 v73, v35 offset:20608
	ds_read_b32 v74, v35 offset:20672
	s_waitcnt lgkmcnt(10)
	v_mfma_f32_16x16x4_f32 v[208:211], v60, v61, v[208:211]
	v_mfma_f32_16x16x4_f32 v[212:215], v60, v62, v[212:215]
	v_mfma_f32_16x16x4_f32 v[216:219], v60, v63, v[216:219]
	v_mfma_f32_16x16x4_f32 v[220:223], v60, v64, v[220:223]
	ds_read_b32 v60, v43 offset:2688
	ds_read_b32 v61, v35 offset:21504
	ds_read_b32 v62, v35 offset:21568
	ds_read_b32 v63, v35 offset:21632
	ds_read_b32 v64, v35 offset:21696
	s_waitcnt lgkmcnt(10)
	v_mfma_f32_16x16x4_f32 v[208:211], v65, v66, v[208:211]
	v_mfma_f32_16x16x4_f32 v[212:215], v65, v67, v[212:215]
	v_mfma_f32_16x16x4_f32 v[216:219], v65, v68, v[216:219]
	v_mfma_f32_16x16x4_f32 v[220:223], v65, v69, v[220:223]
	ds_read_b32 v65, v43 offset:2816
	ds_read_b32 v66, v35 offset:22528
	ds_read_b32 v67, v35 offset:22592
	ds_read_b32 v68, v35 offset:22656
	ds_read_b32 v69, v35 offset:22720
	s_waitcnt lgkmcnt(10)
	v_mfma_f32_16x16x4_f32 v[208:211], v70, v71, v[208:211]
	v_mfma_f32_16x16x4_f32 v[212:215], v70, v72, v[212:215]
	v_mfma_f32_16x16x4_f32 v[216:219], v70, v73, v[216:219]
	v_mfma_f32_16x16x4_f32 v[220:223], v70, v74, v[220:223]
	ds_read_b32 v70, v43 offset:2944
	ds_read_b32 v71, v35 offset:23552
	ds_read_b32 v72, v35 offset:23616
	ds_read_b32 v73, v35 offset:23680
	ds_read_b32 v74, v35 offset:23744
	s_waitcnt lgkmcnt(10)
	v_mfma_f32_16x16x4_f32 v[208:211], v60, v61, v[208:211]
	v_mfma_f32_16x16x4_f32 v[212:215], v60, v62, v[212:215]
	v_mfma_f32_16x16x4_f32 v[216:219], v60, v63, v[216:219]
	v_mfma_f32_16x16x4_f32 v[220:223], v60, v64, v[220:223]
	ds_read_b32 v60, v43 offset:3072
	ds_read_b32 v61, v35 offset:24576
	ds_read_b32 v62, v35 offset:24640
	ds_read_b32 v63, v35 offset:24704
	ds_read_b32 v64, v35 offset:24768
	s_waitcnt lgkmcnt(10)
	v_mfma_f32_16x16x4_f32 v[208:211], v65, v66, v[208:211]
	v_mfma_f32_16x16x4_f32 v[212:215], v65, v67, v[212:215]
	v_mfma_f32_16x16x4_f32 v[216:219], v65, v68, v[216:219]
	v_mfma_f32_16x16x4_f32 v[220:223], v65, v69, v[220:223]
	ds_read_b32 v65, v43 offset:3200
	ds_read_b32 v66, v35 offset:25600
	ds_read_b32 v67, v35 offset:25664
	ds_read_b32 v68, v35 offset:25728
	ds_read_b32 v69, v35 offset:25792
	s_waitcnt lgkmcnt(10)
	v_mfma_f32_16x16x4_f32 v[208:211], v70, v71, v[208:211]
	v_mfma_f32_16x16x4_f32 v[212:215], v70, v72, v[212:215]
	v_mfma_f32_16x16x4_f32 v[216:219], v70, v73, v[216:219]
	v_mfma_f32_16x16x4_f32 v[220:223], v70, v74, v[220:223]
	ds_read_b32 v70, v43 offset:3328
	ds_read_b32 v71, v35 offset:26624
	ds_read_b32 v72, v35 offset:26688
	ds_read_b32 v73, v35 offset:26752
	ds_read_b32 v74, v35 offset:26816
	s_waitcnt lgkmcnt(10)
	v_mfma_f32_16x16x4_f32 v[208:211], v60, v61, v[208:211]
	v_mfma_f32_16x16x4_f32 v[212:215], v60, v62, v[212:215]
	v_mfma_f32_16x16x4_f32 v[216:219], v60, v63, v[216:219]
	v_mfma_f32_16x16x4_f32 v[220:223], v60, v64, v[220:223]
	ds_read_b32 v60, v43 offset:3456
	ds_read_b32 v61, v35 offset:27648
	ds_read_b32 v62, v35 offset:27712
	ds_read_b32 v63, v35 offset:27776
	ds_read_b32 v64, v35 offset:27840
	s_waitcnt lgkmcnt(10)
	v_mfma_f32_16x16x4_f32 v[208:211], v65, v66, v[208:211]
	v_mfma_f32_16x16x4_f32 v[212:215], v65, v67, v[212:215]
	v_mfma_f32_16x16x4_f32 v[216:219], v65, v68, v[216:219]
	v_mfma_f32_16x16x4_f32 v[220:223], v65, v69, v[220:223]
	ds_read_b32 v65, v43 offset:3584
	ds_read_b32 v66, v35 offset:28672
	ds_read_b32 v67, v35 offset:28736
	ds_read_b32 v68, v35 offset:28800
	ds_read_b32 v69, v35 offset:28864
	s_waitcnt lgkmcnt(10)
	v_mfma_f32_16x16x4_f32 v[208:211], v70, v71, v[208:211]
	v_mfma_f32_16x16x4_f32 v[212:215], v70, v72, v[212:215]
	v_mfma_f32_16x16x4_f32 v[216:219], v70, v73, v[216:219]
	v_mfma_f32_16x16x4_f32 v[220:223], v70, v74, v[220:223]
	ds_read_b32 v70, v43 offset:3712
	ds_read_b32 v71, v35 offset:29696
	ds_read_b32 v72, v35 offset:29760
	ds_read_b32 v73, v35 offset:29824
	ds_read_b32 v74, v35 offset:29888
	s_waitcnt lgkmcnt(10)
	v_mfma_f32_16x16x4_f32 v[208:211], v60, v61, v[208:211]
	v_mfma_f32_16x16x4_f32 v[212:215], v60, v62, v[212:215]
	v_mfma_f32_16x16x4_f32 v[216:219], v60, v63, v[216:219]
	v_mfma_f32_16x16x4_f32 v[220:223], v60, v64, v[220:223]
	ds_read_b32 v60, v43 offset:3840
	ds_read_b32 v61, v35 offset:30720
	ds_read_b32 v62, v35 offset:30784
	ds_read_b32 v63, v35 offset:30848
	ds_read_b32 v64, v35 offset:30912
	s_waitcnt lgkmcnt(10)
	v_mfma_f32_16x16x4_f32 v[208:211], v65, v66, v[208:211]
	v_mfma_f32_16x16x4_f32 v[212:215], v65, v67, v[212:215]
	v_mfma_f32_16x16x4_f32 v[216:219], v65, v68, v[216:219]
	v_mfma_f32_16x16x4_f32 v[220:223], v65, v69, v[220:223]
	ds_read_b32 v65, v43 offset:3968
	ds_read_b32 v66, v35 offset:31744
	ds_read_b32 v67, v35 offset:31808
	ds_read_b32 v68, v35 offset:31872
	ds_read_b32 v69, v35 offset:31936
	s_waitcnt lgkmcnt(10)
	v_mfma_f32_16x16x4_f32 v[208:211], v70, v71, v[208:211]
	v_mfma_f32_16x16x4_f32 v[212:215], v70, v72, v[212:215]
	v_mfma_f32_16x16x4_f32 v[216:219], v70, v73, v[216:219]
	v_mfma_f32_16x16x4_f32 v[220:223], v70, v74, v[220:223]
	ds_read_b32 v70, v42 offset:0
	ds_read_b32 v71, v35 offset:32768
	ds_read_b32 v72, v35 offset:32832
	ds_read_b32 v73, v35 offset:32896
	ds_read_b32 v74, v35 offset:32960
	s_waitcnt lgkmcnt(10)
	v_mfma_f32_16x16x4_f32 v[208:211], v60, v61, v[208:211]
	v_mfma_f32_16x16x4_f32 v[212:215], v60, v62, v[212:215]
	v_mfma_f32_16x16x4_f32 v[216:219], v60, v63, v[216:219]
	v_mfma_f32_16x16x4_f32 v[220:223], v60, v64, v[220:223]
	ds_read_b32 v60, v42 offset:128
	ds_read_b32 v61, v35 offset:33792
	ds_read_b32 v62, v35 offset:33856
	ds_read_b32 v63, v35 offset:33920
	ds_read_b32 v64, v35 offset:33984
	s_waitcnt lgkmcnt(10)
	v_mfma_f32_16x16x4_f32 v[208:211], v65, v66, v[208:211]
	v_mfma_f32_16x16x4_f32 v[212:215], v65, v67, v[212:215]
	v_mfma_f32_16x16x4_f32 v[216:219], v65, v68, v[216:219]
	v_mfma_f32_16x16x4_f32 v[220:223], v65, v69, v[220:223]
	s_waitcnt lgkmcnt(5)
	v_mfma_f32_16x16x4_f32 v[208:211], v70, v71, v[208:211]
	v_mfma_f32_16x16x4_f32 v[212:215], v70, v72, v[212:215]
	v_mfma_f32_16x16x4_f32 v[216:219], v70, v73, v[216:219]
	v_mfma_f32_16x16x4_f32 v[220:223], v70, v74, v[220:223]
	s_waitcnt lgkmcnt(0)
	v_mfma_f32_16x16x4_f32 v[208:211], v60, v61, v[208:211]
	v_mfma_f32_16x16x4_f32 v[212:215], v60, v62, v[212:215]
	v_mfma_f32_16x16x4_f32 v[216:219], v60, v63, v[216:219]
	v_mfma_f32_16x16x4_f32 v[220:223], v60, v64, v[220:223]
	v_bfe_u32 v38, v108, 4, 1
	v_cmp_eq_u32_e64 s[44:45], 1, v38
	s_lshl_b32 s26, s16, 11
	s_mov_b32 s27, 0
	v_mul_u32_u24_e32 v38, 0x1fe0, v38
	v_mov_b32_e32 v39, 0
	v_cndmask_b32_e64 v224, v200, v204, s[44:45]
	v_cndmask_b32_e64 v225, v201, v205, s[44:45]
	v_cndmask_b32_e64 v226, v202, v206, s[44:45]
	v_cndmask_b32_e64 v227, v203, v207, s[44:45]
	v_lshl_add_u64 v[40:41], v[8:9], 0, v[38:39]
	v_lshl_add_u64 v[40:41], v[40:41], 0, s[26:27]
	s_mov_b64 s[26:27], 0x1000
	v_lshl_add_u64 v[42:43], v[40:41], 0, s[26:27]
	s_mov_b64 s[46:47], exec
	s_mov_b32 exec_hi, 0
	s_nop 7
	s_nop 7
	v_div_scale_f32 v60, s[26:27], v224, v224, v208
	v_rcp_f32_e32 v61, v60
	s_nop 0
	v_fma_f32 v62, -v60, v61, 1.0
	v_fmac_f32_e32 v61, v62, v61
	v_div_scale_f32 v62, vcc, v208, v224, v208
	v_mul_f32_e32 v63, v62, v61
	v_fma_f32 v64, -v60, v63, v62
	v_fmac_f32_e32 v63, v64, v61
	v_fma_f32 v60, -v60, v63, v62
	v_div_fmas_f32 v60, v60, v61, v63
	v_div_fixup_f32 v60, v60, v224, v208
	v_bfe_u32 v61, v60, 16, 1
	v_add3_u32 v61, v60, v61, s48
	flat_store_short_d16_hi v[40:41], v61 offset:0
	v_div_scale_f32 v60, s[26:27], v225, v225, v209
	v_rcp_f32_e32 v61, v60
	s_nop 0
	v_fma_f32 v62, -v60, v61, 1.0
	v_fmac_f32_e32 v61, v62, v61
	v_div_scale_f32 v62, vcc, v209, v225, v209
	v_mul_f32_e32 v63, v62, v61
	v_fma_f32 v64, -v60, v63, v62
	v_fmac_f32_e32 v63, v64, v61
	v_fma_f32 v60, -v60, v63, v62
	v_div_fmas_f32 v60, v60, v61, v63
	v_div_fixup_f32 v60, v60, v225, v209
	v_bfe_u32 v61, v60, 16, 1
	v_add3_u32 v61, v60, v61, s48
	flat_store_short_d16_hi v[40:41], v61 offset:2048
	v_div_scale_f32 v60, s[26:27], v226, v226, v210
	v_rcp_f32_e32 v61, v60
	s_nop 0
	v_fma_f32 v62, -v60, v61, 1.0
	v_fmac_f32_e32 v61, v62, v61
	v_div_scale_f32 v62, vcc, v210, v226, v210
	v_mul_f32_e32 v63, v62, v61
	v_fma_f32 v64, -v60, v63, v62
	v_fmac_f32_e32 v63, v64, v61
	v_fma_f32 v60, -v60, v63, v62
	v_div_fmas_f32 v60, v60, v61, v63
	v_div_fixup_f32 v60, v60, v226, v210
	v_bfe_u32 v61, v60, 16, 1
	v_add3_u32 v61, v60, v61, s48
	flat_store_short_d16_hi v[42:43], v61 offset:0
	v_div_scale_f32 v60, s[26:27], v227, v227, v211
	v_rcp_f32_e32 v61, v60
	s_nop 0
	v_fma_f32 v62, -v60, v61, 1.0
	v_fmac_f32_e32 v61, v62, v61
	v_div_scale_f32 v62, vcc, v211, v227, v211
	v_mul_f32_e32 v63, v62, v61
	v_fma_f32 v64, -v60, v63, v62
	v_fmac_f32_e32 v63, v64, v61
	v_fma_f32 v60, -v60, v63, v62
	v_div_fmas_f32 v60, v60, v61, v63
	v_div_fixup_f32 v60, v60, v227, v211
	v_bfe_u32 v61, v60, 16, 1
	v_add3_u32 v61, v60, v61, s48
	flat_store_short_d16_hi v[42:43], v61 offset:2048
	v_div_scale_f32 v60, s[26:27], v224, v224, v212
	v_rcp_f32_e32 v61, v60
	s_nop 0
	v_fma_f32 v62, -v60, v61, 1.0
	v_fmac_f32_e32 v61, v62, v61
	v_div_scale_f32 v62, vcc, v212, v224, v212
	v_mul_f32_e32 v63, v62, v61
	v_fma_f32 v64, -v60, v63, v62
	v_fmac_f32_e32 v63, v64, v61
	v_fma_f32 v60, -v60, v63, v62
	v_div_fmas_f32 v60, v60, v61, v63
	v_div_fixup_f32 v60, v60, v224, v212
	v_bfe_u32 v61, v60, 16, 1
	v_add3_u32 v61, v60, v61, s48
	flat_store_short_d16_hi v[40:41], v61 offset:32
	v_div_scale_f32 v60, s[26:27], v225, v225, v213
	v_rcp_f32_e32 v61, v60
	s_nop 0
	v_fma_f32 v62, -v60, v61, 1.0
	v_fmac_f32_e32 v61, v62, v61
	v_div_scale_f32 v62, vcc, v213, v225, v213
	v_mul_f32_e32 v63, v62, v61
	v_fma_f32 v64, -v60, v63, v62
	v_fmac_f32_e32 v63, v64, v61
	v_fma_f32 v60, -v60, v63, v62
	v_div_fmas_f32 v60, v60, v61, v63
	v_div_fixup_f32 v60, v60, v225, v213
	v_bfe_u32 v61, v60, 16, 1
	v_add3_u32 v61, v60, v61, s48
	flat_store_short_d16_hi v[40:41], v61 offset:2080
	v_div_scale_f32 v60, s[26:27], v226, v226, v214
	v_rcp_f32_e32 v61, v60
	s_nop 0
	v_fma_f32 v62, -v60, v61, 1.0
	v_fmac_f32_e32 v61, v62, v61
	v_div_scale_f32 v62, vcc, v214, v226, v214
	v_mul_f32_e32 v63, v62, v61
	v_fma_f32 v64, -v60, v63, v62
	v_fmac_f32_e32 v63, v64, v61
	v_fma_f32 v60, -v60, v63, v62
	v_div_fmas_f32 v60, v60, v61, v63
	v_div_fixup_f32 v60, v60, v226, v214
	v_bfe_u32 v61, v60, 16, 1
	v_add3_u32 v61, v60, v61, s48
	flat_store_short_d16_hi v[42:43], v61 offset:32
	v_div_scale_f32 v60, s[26:27], v227, v227, v215
	v_rcp_f32_e32 v61, v60
	s_nop 0
	v_fma_f32 v62, -v60, v61, 1.0
	v_fmac_f32_e32 v61, v62, v61
	v_div_scale_f32 v62, vcc, v215, v227, v215
	v_mul_f32_e32 v63, v62, v61
	v_fma_f32 v64, -v60, v63, v62
	v_fmac_f32_e32 v63, v64, v61
	v_fma_f32 v60, -v60, v63, v62
	v_div_fmas_f32 v60, v60, v61, v63
	v_div_fixup_f32 v60, v60, v227, v215
	v_bfe_u32 v61, v60, 16, 1
	v_add3_u32 v61, v60, v61, s48
	flat_store_short_d16_hi v[42:43], v61 offset:2080
	v_div_scale_f32 v60, s[26:27], v224, v224, v216
	v_rcp_f32_e32 v61, v60
	s_nop 0
	v_fma_f32 v62, -v60, v61, 1.0
	v_fmac_f32_e32 v61, v62, v61
	v_div_scale_f32 v62, vcc, v216, v224, v216
	v_mul_f32_e32 v63, v62, v61
	v_fma_f32 v64, -v60, v63, v62
	v_fmac_f32_e32 v63, v64, v61
	v_fma_f32 v60, -v60, v63, v62
	v_div_fmas_f32 v60, v60, v61, v63
	v_div_fixup_f32 v60, v60, v224, v216
	v_bfe_u32 v61, v60, 16, 1
	v_add3_u32 v61, v60, v61, s48
	flat_store_short_d16_hi v[40:41], v61 offset:64
	v_div_scale_f32 v60, s[26:27], v225, v225, v217
	v_rcp_f32_e32 v61, v60
	s_nop 0
	v_fma_f32 v62, -v60, v61, 1.0
	v_fmac_f32_e32 v61, v62, v61
	v_div_scale_f32 v62, vcc, v217, v225, v217
	v_mul_f32_e32 v63, v62, v61
	v_fma_f32 v64, -v60, v63, v62
	v_fmac_f32_e32 v63, v64, v61
	v_fma_f32 v60, -v60, v63, v62
	v_div_fmas_f32 v60, v60, v61, v63
	v_div_fixup_f32 v60, v60, v225, v217
	v_bfe_u32 v61, v60, 16, 1
	v_add3_u32 v61, v60, v61, s48
	flat_store_short_d16_hi v[40:41], v61 offset:2112
	v_div_scale_f32 v60, s[26:27], v226, v226, v218
	v_rcp_f32_e32 v61, v60
	s_nop 0
	v_fma_f32 v62, -v60, v61, 1.0
	v_fmac_f32_e32 v61, v62, v61
	v_div_scale_f32 v62, vcc, v218, v226, v218
	v_mul_f32_e32 v63, v62, v61
	v_fma_f32 v64, -v60, v63, v62
	v_fmac_f32_e32 v63, v64, v61
	v_fma_f32 v60, -v60, v63, v62
	v_div_fmas_f32 v60, v60, v61, v63
	v_div_fixup_f32 v60, v60, v226, v218
	v_bfe_u32 v61, v60, 16, 1
	v_add3_u32 v61, v60, v61, s48
	flat_store_short_d16_hi v[42:43], v61 offset:64
	v_div_scale_f32 v60, s[26:27], v227, v227, v219
	v_rcp_f32_e32 v61, v60
	s_nop 0
	v_fma_f32 v62, -v60, v61, 1.0
	v_fmac_f32_e32 v61, v62, v61
	v_div_scale_f32 v62, vcc, v219, v227, v219
	v_mul_f32_e32 v63, v62, v61
	v_fma_f32 v64, -v60, v63, v62
	v_fmac_f32_e32 v63, v64, v61
	v_fma_f32 v60, -v60, v63, v62
	v_div_fmas_f32 v60, v60, v61, v63
	v_div_fixup_f32 v60, v60, v227, v219
	v_bfe_u32 v61, v60, 16, 1
	v_add3_u32 v61, v60, v61, s48
	flat_store_short_d16_hi v[42:43], v61 offset:2112
	v_div_scale_f32 v60, s[26:27], v224, v224, v220
	v_rcp_f32_e32 v61, v60
	s_nop 0
	v_fma_f32 v62, -v60, v61, 1.0
	v_fmac_f32_e32 v61, v62, v61
	v_div_scale_f32 v62, vcc, v220, v224, v220
	v_mul_f32_e32 v63, v62, v61
	v_fma_f32 v64, -v60, v63, v62
	v_fmac_f32_e32 v63, v64, v61
	v_fma_f32 v60, -v60, v63, v62
	v_div_fmas_f32 v60, v60, v61, v63
	v_div_fixup_f32 v60, v60, v224, v220
	v_bfe_u32 v61, v60, 16, 1
	v_add3_u32 v61, v60, v61, s48
	flat_store_short_d16_hi v[40:41], v61 offset:96
	v_div_scale_f32 v60, s[26:27], v225, v225, v221
	v_rcp_f32_e32 v61, v60
	s_nop 0
	v_fma_f32 v62, -v60, v61, 1.0
	v_fmac_f32_e32 v61, v62, v61
	v_div_scale_f32 v62, vcc, v221, v225, v221
	v_mul_f32_e32 v63, v62, v61
	v_fma_f32 v64, -v60, v63, v62
	v_fmac_f32_e32 v63, v64, v61
	v_fma_f32 v60, -v60, v63, v62
	v_div_fmas_f32 v60, v60, v61, v63
	v_div_fixup_f32 v60, v60, v225, v221
	v_bfe_u32 v61, v60, 16, 1
	v_add3_u32 v61, v60, v61, s48
	flat_store_short_d16_hi v[40:41], v61 offset:2144
	v_div_scale_f32 v60, s[26:27], v226, v226, v222
	v_rcp_f32_e32 v61, v60
	s_nop 0
	v_fma_f32 v62, -v60, v61, 1.0
	v_fmac_f32_e32 v61, v62, v61
	v_div_scale_f32 v62, vcc, v222, v226, v222
	v_mul_f32_e32 v63, v62, v61
	v_fma_f32 v64, -v60, v63, v62
	v_fmac_f32_e32 v63, v64, v61
	v_fma_f32 v60, -v60, v63, v62
	v_div_fmas_f32 v60, v60, v61, v63
	v_div_fixup_f32 v60, v60, v226, v222
	v_bfe_u32 v61, v60, 16, 1
	v_add3_u32 v61, v60, v61, s48
	flat_store_short_d16_hi v[42:43], v61 offset:96
	v_div_scale_f32 v60, s[26:27], v227, v227, v223
	v_rcp_f32_e32 v61, v60
	s_nop 0
	v_fma_f32 v62, -v60, v61, 1.0
	v_fmac_f32_e32 v61, v62, v61
	v_div_scale_f32 v62, vcc, v223, v227, v223
	v_mul_f32_e32 v63, v62, v61
	v_fma_f32 v64, -v60, v63, v62
	v_fmac_f32_e32 v63, v64, v61
	v_fma_f32 v60, -v60, v63, v62
	v_div_fmas_f32 v60, v60, v61, v63
	v_div_fixup_f32 v60, v60, v227, v223
	v_bfe_u32 v61, v60, 16, 1
	v_add3_u32 v61, v60, v61, s48
	flat_store_short_d16_hi v[42:43], v61 offset:2144
	s_mov_b64 exec, s[46:47]
	s_add_i32 s15, s15, s74
	s_cmpk_gt_i32 s15, 0xff
	s_waitcnt lgkmcnt(0)
	s_barrier
	s_cbranch_scc0 .LBB0_689
